# GEMM K-loops: second K-step of a trip uses offset:128, the eight 64-bit tile pointers advance once per trip (8 fewer 64-bit VALU adds per trip)
# speedup vs baseline: 1.0010x; 1.0010x over previous
; #define MFMA(a, b, c) __builtin_amdgcn_mfma_f32_32x32x16_bf16((a), (b), (c), 0, 0, 0)
; template <bool AT>
; DI void gemm_main(f32x16 (&acc)[2][4], const u16* __restrict__ R, int ldr, const u16* __restrict__ Cm, int ldc,
;                   const u16* __restrict__ RT, int ldrt, int K, char* smem, int tid) {
;     ...
;     if (kt + 2 < nk) {
;       const int kn = kt + 2;
; #pragma unroll
;       for (int i = 0; i < 4; ++i) {
;         const int cid = tid + NT * i;
;         const int row = cid >> 3, kc = cid & 7;
;         if (AT && kn < 8) {
;           const int kr = cid >> 5, tc = cid & 31;
;           rr[i] = *(const u32x4*)(RT + (size_t)(kn * 64 + kr) * ldrt + tc * 8);
;         } else {
;           rr[i] = *(const u32x4*)(R + (size_t)row * ldr + kn * 64 + kc * 8);
;         }
;         cr[i] = *(const u32x4*)(Cm + (size_t)row * ldc + kn * 64 + kc * 8);
;       }
;     }
;     __builtin_amdgcn_sched_barrier(0x38F);
;     if (kt >= 0) {
;       const u16* Rs = S0 + (kt & 1) * STG;
;       const u16* Cs = Rs + 256 * 72;
;       const u16* RTs = Rs;
; #pragma unroll
;       for (int ks = 0; ks < 4; ++ks) {
;         bf16x8 rf[2];
; #pragma unroll
;         for (int rb = 0; rb < 2; ++rb) {
;           if (AT && kt < 8) {
;             const u16* src = RTs + (16 * ks + 8 * g) * 264 + 64 * wr + 32 * rb + li;
;             bf16x8 t;
; #pragma unroll
;             for (int j = 0; j < 8; ++j) t[j] = (short)src[j * 264];
;             rf[rb] = t;
;           } else {
;             rf[rb] = *(const bf16x8*)(Rs + (64 * wr + 32 * rb + li) * 72 + 16 * ks + 8 * g);
;           }
;         }
; #pragma unroll
;         for (int cb = 0; cb < 4; ++cb) {
;           const bf16x8 cfv = *(const bf16x8*)(Cs + (128 * wc + 32 * cb + li) * 72 + 16 * ks + 8 * g);
; #pragma unroll
;           for (int rb = 0; rb < 2; ++rb) acc[rb][cb] = MFMA(rf[rb], cfv, acc[rb][cb]);
;         }
;       }
;     }
;     __syncthreads();
.Lgt_loop:
	ds_read_b128 v[192:195], v187 offset:0
	ds_read_b128 v[220:223], v187 offset:4608
	ds_read_b128 v[232:235], v190 offset:36864
	ds_read_b128 v[236:239], v190 offset:41472
	ds_read_b128 v[240:243], v190 offset:46080
	ds_read_b128 v[244:247], v190 offset:50688
	ds_read_b128 v[224:227], v187 offset:32
	ds_read_b128 v[228:231], v187 offset:4640
	s_waitcnt lgkmcnt(5)
	v_mfma_f32_32x32x16_bf16 v[112:127], v[192:195], v[232:235], v[112:127]
	v_mfma_f32_32x32x16_bf16 v[48:63], v[220:223], v[232:235], v[48:63]
	ds_read_b128 v[232:235], v190 offset:36896
	s_waitcnt vmcnt(0)
	ds_write_b128 v191, v[144:147]
	s_waitcnt lgkmcnt(6)
	v_mfma_f32_32x32x16_bf16 v[96:111], v[192:195], v[236:239], v[96:111]
	v_mfma_f32_32x32x16_bf16 v[32:47], v[220:223], v[236:239], v[32:47]
	ds_read_b128 v[236:239], v190 offset:41504
	ds_write_b128 v191, v[152:155] offset:36864
	s_waitcnt lgkmcnt(7)
	v_mfma_f32_32x32x16_bf16 v[80:95], v[192:195], v[240:243], v[80:95]
	v_mfma_f32_32x32x16_bf16 v[16:31], v[220:223], v[240:243], v[16:31]
	ds_read_b128 v[240:243], v190 offset:46112
	ds_write_b128 v196, v[136:139]
	s_waitcnt lgkmcnt(8)
	v_mfma_f32_32x32x16_bf16 v[64:79], v[192:195], v[244:247], v[64:79]
	v_mfma_f32_32x32x16_bf16 v[0:15], v[220:223], v[244:247], v[0:15]
	ds_read_b128 v[244:247], v190 offset:50720
	ds_write_b128 v196, v[148:151] offset:36864
	ds_read_b128 v[192:195], v187 offset:64
	ds_read_b128 v[220:223], v187 offset:4672
	s_waitcnt lgkmcnt(9)
	v_mfma_f32_32x32x16_bf16 v[112:127], v[224:227], v[232:235], v[112:127]
	v_mfma_f32_32x32x16_bf16 v[48:63], v[228:231], v[232:235], v[48:63]
	ds_read_b128 v[232:235], v190 offset:36928
	ds_write_b128 v197, v[132:135]
	s_waitcnt lgkmcnt(9)
	v_mfma_f32_32x32x16_bf16 v[96:111], v[224:227], v[236:239], v[96:111]
	v_mfma_f32_32x32x16_bf16 v[32:47], v[228:231], v[236:239], v[32:47]
	ds_read_b128 v[236:239], v190 offset:41536
	ds_write_b128 v197, v[140:143] offset:36864
	s_waitcnt lgkmcnt(9)
	v_mfma_f32_32x32x16_bf16 v[80:95], v[224:227], v[240:243], v[80:95]
	v_mfma_f32_32x32x16_bf16 v[16:31], v[228:231], v[240:243], v[16:31]
	ds_read_b128 v[240:243], v190 offset:46144
	ds_write_b128 v249, v[128:131]
	s_waitcnt lgkmcnt(9)
	v_mfma_f32_32x32x16_bf16 v[64:79], v[224:227], v[244:247], v[64:79]
	v_mfma_f32_32x32x16_bf16 v[0:15], v[228:231], v[244:247], v[0:15]
	ds_read_b128 v[244:247], v190 offset:50752
	ds_write_b128 v249, v[156:159] offset:36864
	ds_read_b128 v[224:227], v187 offset:96
	ds_read_b128 v[228:231], v187 offset:4704
	s_waitcnt lgkmcnt(9)
	v_mfma_f32_32x32x16_bf16 v[112:127], v[192:195], v[232:235], v[112:127]
	v_mfma_f32_32x32x16_bf16 v[48:63], v[220:223], v[232:235], v[48:63]
	ds_read_b128 v[232:235], v190 offset:36960
	v_subrev_u32_e32 v191, 0x12000, v191
	global_load_dwordx4 v[144:147], v[174:175], off
	s_waitcnt lgkmcnt(8)
	v_mfma_f32_32x32x16_bf16 v[96:111], v[192:195], v[236:239], v[96:111]
	v_mfma_f32_32x32x16_bf16 v[32:47], v[220:223], v[236:239], v[32:47]
	ds_read_b128 v[236:239], v190 offset:41568
	v_subrev_u32_e32 v196, 0x12000, v196
	global_load_dwordx4 v[152:155], v[166:167], off
	s_waitcnt lgkmcnt(7)
	v_mfma_f32_32x32x16_bf16 v[80:95], v[192:195], v[240:243], v[80:95]
	v_mfma_f32_32x32x16_bf16 v[16:31], v[220:223], v[240:243], v[16:31]
	ds_read_b128 v[240:243], v190 offset:46176
	v_subrev_u32_e32 v197, 0x12000, v197
	global_load_dwordx4 v[136:139], v[172:173], off
	s_waitcnt lgkmcnt(6)
	v_mfma_f32_32x32x16_bf16 v[64:79], v[192:195], v[244:247], v[64:79]
	v_mfma_f32_32x32x16_bf16 v[0:15], v[220:223], v[244:247], v[0:15]
	ds_read_b128 v[244:247], v190 offset:50784
	v_subrev_u32_e32 v249, 0x12000, v249
	global_load_dwordx4 v[148:151], v[164:165], off
	v_add_u32_e32 v187, 0x12000, v187
	v_add_u32_e32 v190, 0x12000, v190
	s_waitcnt lgkmcnt(3)
	v_mfma_f32_32x32x16_bf16 v[112:127], v[224:227], v[232:235], v[112:127]
	v_mfma_f32_32x32x16_bf16 v[48:63], v[228:231], v[232:235], v[48:63]
	global_load_dwordx4 v[132:135], v[170:171], off
	s_waitcnt lgkmcnt(2)
	v_mfma_f32_32x32x16_bf16 v[96:111], v[224:227], v[236:239], v[96:111]
	v_mfma_f32_32x32x16_bf16 v[32:47], v[228:231], v[236:239], v[32:47]
	global_load_dwordx4 v[140:143], v[162:163], off
	s_waitcnt lgkmcnt(1)
	v_mfma_f32_32x32x16_bf16 v[80:95], v[224:227], v[240:243], v[80:95]
	v_mfma_f32_32x32x16_bf16 v[16:31], v[228:231], v[240:243], v[16:31]
	global_load_dwordx4 v[128:131], v[168:169], off
	s_waitcnt lgkmcnt(0)
	v_mfma_f32_32x32x16_bf16 v[64:79], v[224:227], v[244:247], v[64:79]
	v_mfma_f32_32x32x16_bf16 v[0:15], v[228:231], v[244:247], v[0:15]
	global_load_dwordx4 v[156:159], v[160:161], off
	s_waitcnt lgkmcnt(0)
	s_barrier
; #define MFMA(a, b, c) __builtin_amdgcn_mfma_f32_32x32x16_bf16((a), (b), (c), 0, 0, 0)
; template <bool AT>
; DI void gemm_main(f32x16 (&acc)[2][4], const u16* __restrict__ R, int ldr, const u16* __restrict__ Cm, int ldc,
;                   const u16* __restrict__ RT, int ldrt, int K, char* smem, int tid) {
;     ...
;     if (kt + 2 < nk) {
;       const int kn = kt + 2;
; #pragma unroll
;       for (int i = 0; i < 4; ++i) {
;         const int cid = tid + NT * i;
;         const int row = cid >> 3, kc = cid & 7;
;         if (AT && kn < 8) {
;           const int kr = cid >> 5, tc = cid & 31;
;           rr[i] = *(const u32x4*)(RT + (size_t)(kn * 64 + kr) * ldrt + tc * 8);
;         } else {
;           rr[i] = *(const u32x4*)(R + (size_t)row * ldr + kn * 64 + kc * 8);
;         }
;         cr[i] = *(const u32x4*)(Cm + (size_t)row * ldc + kn * 64 + kc * 8);
;       }
;     }
;     __builtin_amdgcn_sched_barrier(0x38F);
;     if (kt >= 0) {
;       const u16* Rs = S0 + (kt & 1) * STG;
;       const u16* Cs = Rs + 256 * 72;
;       const u16* RTs = Rs;
; #pragma unroll
;       for (int ks = 0; ks < 4; ++ks) {
;         bf16x8 rf[2];
; #pragma unroll
;         for (int rb = 0; rb < 2; ++rb) {
;           if (AT && kt < 8) {
;             const u16* src = RTs + (16 * ks + 8 * g) * 264 + 64 * wr + 32 * rb + li;
;             bf16x8 t;
; #pragma unroll
;             for (int j = 0; j < 8; ++j) t[j] = (short)src[j * 264];
;             rf[rb] = t;
;           } else {
;             rf[rb] = *(const bf16x8*)(Rs + (64 * wr + 32 * rb + li) * 72 + 16 * ks + 8 * g);
;           }
;         }
; #pragma unroll
;         for (int cb = 0; cb < 4; ++cb) {
;           const bf16x8 cfv = *(const bf16x8*)(Cs + (128 * wc + 32 * cb + li) * 72 + 16 * ks + 8 * g);
; #pragma unroll
;           for (int rb = 0; rb < 2; ++rb) acc[rb][cb] = MFMA(rf[rb], cfv, acc[rb][cb]);
;         }
;       }
;     }
;     __syncthreads();
;   }
	ds_read_b128 v[192:195], v187 offset:0
	ds_read_b128 v[220:223], v187 offset:4608
	ds_read_b128 v[232:235], v190 offset:36864
	ds_read_b128 v[236:239], v190 offset:41472
	ds_read_b128 v[240:243], v190 offset:46080
	ds_read_b128 v[244:247], v190 offset:50688
	ds_read_b128 v[224:227], v187 offset:32
	ds_read_b128 v[228:231], v187 offset:4640
	s_waitcnt lgkmcnt(5)
	v_mfma_f32_32x32x16_bf16 v[112:127], v[192:195], v[232:235], v[112:127]
	v_mfma_f32_32x32x16_bf16 v[48:63], v[220:223], v[232:235], v[48:63]
	ds_read_b128 v[232:235], v190 offset:36896
	s_waitcnt vmcnt(0)
	ds_write_b128 v191, v[144:147]
	s_waitcnt lgkmcnt(6)
	v_mfma_f32_32x32x16_bf16 v[96:111], v[192:195], v[236:239], v[96:111]
	v_mfma_f32_32x32x16_bf16 v[32:47], v[220:223], v[236:239], v[32:47]
	ds_read_b128 v[236:239], v190 offset:41504
	ds_write_b128 v191, v[152:155] offset:36864
	s_waitcnt lgkmcnt(7)
	v_mfma_f32_32x32x16_bf16 v[80:95], v[192:195], v[240:243], v[80:95]
	v_mfma_f32_32x32x16_bf16 v[16:31], v[220:223], v[240:243], v[16:31]
	ds_read_b128 v[240:243], v190 offset:46112
	ds_write_b128 v196, v[136:139]
	s_waitcnt lgkmcnt(8)
	v_mfma_f32_32x32x16_bf16 v[64:79], v[192:195], v[244:247], v[64:79]
	v_mfma_f32_32x32x16_bf16 v[0:15], v[220:223], v[244:247], v[0:15]
	ds_read_b128 v[244:247], v190 offset:50720
	ds_write_b128 v196, v[148:151] offset:36864
	ds_read_b128 v[192:195], v187 offset:64
	ds_read_b128 v[220:223], v187 offset:4672
	s_waitcnt lgkmcnt(9)
	v_mfma_f32_32x32x16_bf16 v[112:127], v[224:227], v[232:235], v[112:127]
	v_mfma_f32_32x32x16_bf16 v[48:63], v[228:231], v[232:235], v[48:63]
	ds_read_b128 v[232:235], v190 offset:36928
	ds_write_b128 v197, v[132:135]
	s_waitcnt lgkmcnt(9)
	v_mfma_f32_32x32x16_bf16 v[96:111], v[224:227], v[236:239], v[96:111]
	v_mfma_f32_32x32x16_bf16 v[32:47], v[228:231], v[236:239], v[32:47]
	ds_read_b128 v[236:239], v190 offset:41536
	ds_write_b128 v197, v[140:143] offset:36864
	s_waitcnt lgkmcnt(9)
	v_mfma_f32_32x32x16_bf16 v[80:95], v[224:227], v[240:243], v[80:95]
	v_mfma_f32_32x32x16_bf16 v[16:31], v[228:231], v[240:243], v[16:31]
	ds_read_b128 v[240:243], v190 offset:46144
	ds_write_b128 v249, v[128:131]
	s_waitcnt lgkmcnt(9)
	v_mfma_f32_32x32x16_bf16 v[64:79], v[224:227], v[244:247], v[64:79]
	v_mfma_f32_32x32x16_bf16 v[0:15], v[228:231], v[244:247], v[0:15]
	ds_read_b128 v[244:247], v190 offset:50752
	ds_write_b128 v249, v[156:159] offset:36864
	ds_read_b128 v[224:227], v187 offset:96
	ds_read_b128 v[228:231], v187 offset:4704
	s_waitcnt lgkmcnt(9)
	v_mfma_f32_32x32x16_bf16 v[112:127], v[192:195], v[232:235], v[112:127]
	v_mfma_f32_32x32x16_bf16 v[48:63], v[220:223], v[232:235], v[48:63]
	ds_read_b128 v[232:235], v190 offset:36960
	v_add_u32_e32 v191, 0x12000, v191
	global_load_dwordx4 v[144:147], v[174:175], off offset:128
	v_lshl_add_u64 v[174:175], s[58:59], 1, v[174:175]
	s_waitcnt lgkmcnt(8)
	v_mfma_f32_32x32x16_bf16 v[96:111], v[192:195], v[236:239], v[96:111]
	v_mfma_f32_32x32x16_bf16 v[32:47], v[220:223], v[236:239], v[32:47]
	ds_read_b128 v[236:239], v190 offset:41568
	v_add_u32_e32 v196, 0x12000, v196
	global_load_dwordx4 v[152:155], v[166:167], off offset:128
	v_lshl_add_u64 v[166:167], s[58:59], 1, v[166:167]
	s_waitcnt lgkmcnt(7)
	v_mfma_f32_32x32x16_bf16 v[80:95], v[192:195], v[240:243], v[80:95]
	v_mfma_f32_32x32x16_bf16 v[16:31], v[220:223], v[240:243], v[16:31]
	ds_read_b128 v[240:243], v190 offset:46176
	v_add_u32_e32 v197, 0x12000, v197
	global_load_dwordx4 v[136:139], v[172:173], off offset:128
	v_lshl_add_u64 v[172:173], s[58:59], 1, v[172:173]
	s_waitcnt lgkmcnt(6)
	v_mfma_f32_32x32x16_bf16 v[64:79], v[192:195], v[244:247], v[64:79]
	v_mfma_f32_32x32x16_bf16 v[0:15], v[220:223], v[244:247], v[0:15]
	ds_read_b128 v[244:247], v190 offset:50784
	v_add_u32_e32 v249, 0x12000, v249
	global_load_dwordx4 v[148:151], v[164:165], off offset:128
	v_lshl_add_u64 v[164:165], s[58:59], 1, v[164:165]
	v_subrev_u32_e32 v187, 0x12000, v187
	v_subrev_u32_e32 v190, 0x12000, v190
	s_waitcnt lgkmcnt(3)
	v_mfma_f32_32x32x16_bf16 v[112:127], v[224:227], v[232:235], v[112:127]
	v_mfma_f32_32x32x16_bf16 v[48:63], v[228:231], v[232:235], v[48:63]
	global_load_dwordx4 v[132:135], v[170:171], off offset:128
	v_lshl_add_u64 v[170:171], s[58:59], 1, v[170:171]
	s_waitcnt lgkmcnt(2)
	v_mfma_f32_32x32x16_bf16 v[96:111], v[224:227], v[236:239], v[96:111]
	v_mfma_f32_32x32x16_bf16 v[32:47], v[228:231], v[236:239], v[32:47]
	global_load_dwordx4 v[140:143], v[162:163], off offset:128
	v_lshl_add_u64 v[162:163], s[58:59], 1, v[162:163]
	s_waitcnt lgkmcnt(1)
	v_mfma_f32_32x32x16_bf16 v[80:95], v[224:227], v[240:243], v[80:95]
	v_mfma_f32_32x32x16_bf16 v[16:31], v[228:231], v[240:243], v[16:31]
	global_load_dwordx4 v[128:131], v[168:169], off offset:128
	v_lshl_add_u64 v[168:169], s[58:59], 1, v[168:169]
	s_waitcnt lgkmcnt(0)
	v_mfma_f32_32x32x16_bf16 v[64:79], v[224:227], v[244:247], v[64:79]
	v_mfma_f32_32x32x16_bf16 v[0:15], v[228:231], v[244:247], v[0:15]
	global_load_dwordx4 v[156:159], v[160:161], off offset:128
	v_lshl_add_u64 v[160:161], s[58:59], 1, v[160:161]
	s_waitcnt lgkmcnt(0)
	s_barrier
	s_add_i32 s78, s78, -1
	s_cmp_lg_u32 s78, 0
	s_cbranch_scc1 .Lgt_loop
; #define MFMA(a, b, c) __builtin_amdgcn_mfma_f32_32x32x16_bf16((a), (b), (c), 0, 0, 0)
; template <bool AT>
; DI void gemm_main(f32x16 (&acc)[2][4], const u16* __restrict__ R, int ldr, const u16* __restrict__ Cm, int ldc,
;                   const u16* __restrict__ RT, int ldrt, int K, char* smem, int tid) {
;     ...
;     if (kt >= 0) {
;       const u16* Rs = S0 + (kt & 1) * STG;
;       const u16* Cs = Rs + 256 * 72;
;       const u16* RTs = Rs;
; #pragma unroll
;       for (int ks = 0; ks < 4; ++ks) {
;         bf16x8 rf[2];
; #pragma unroll
;         for (int rb = 0; rb < 2; ++rb) {
;           if (AT && kt < 8) {
;             const u16* src = RTs + (16 * ks + 8 * g) * 264 + 64 * wr + 32 * rb + li;
;             bf16x8 t;
; #pragma unroll
;             for (int j = 0; j < 8; ++j) t[j] = (short)src[j * 264];
;             rf[rb] = t;
;           } else {
;             rf[rb] = *(const bf16x8*)(Rs + (64 * wr + 32 * rb + li) * 72 + 16 * ks + 8 * g);
;           }
;         }
; #pragma unroll
;         for (int cb = 0; cb < 4; ++cb) {
;           const bf16x8 cfv = *(const bf16x8*)(Cs + (128 * wc + 32 * cb + li) * 72 + 16 * ks + 8 * g);
; #pragma unroll
;           for (int rb = 0; rb < 2; ++rb) acc[rb][cb] = MFMA(rf[rb], cfv, acc[rb][cb]);
;         }
;       }
;     }
;     __syncthreads();
;   }
	ds_read_b128 v[192:195], v187 offset:0
	ds_read_b128 v[220:223], v187 offset:4608
	ds_read_b128 v[232:235], v190 offset:36864
	ds_read_b128 v[236:239], v190 offset:41472
	ds_read_b128 v[240:243], v190 offset:46080
	ds_read_b128 v[244:247], v190 offset:50688
	ds_read_b128 v[224:227], v187 offset:32
	ds_read_b128 v[228:231], v187 offset:4640
	s_waitcnt lgkmcnt(5)
	v_mfma_f32_32x32x16_bf16 v[112:127], v[192:195], v[232:235], v[112:127]
	v_mfma_f32_32x32x16_bf16 v[48:63], v[220:223], v[232:235], v[48:63]
	ds_read_b128 v[232:235], v190 offset:36896
	s_waitcnt vmcnt(0)
	ds_write_b128 v191, v[144:147]
	s_waitcnt lgkmcnt(6)
	v_mfma_f32_32x32x16_bf16 v[96:111], v[192:195], v[236:239], v[96:111]
	v_mfma_f32_32x32x16_bf16 v[32:47], v[220:223], v[236:239], v[32:47]
	ds_read_b128 v[236:239], v190 offset:41504
	ds_write_b128 v191, v[152:155] offset:36864
	s_waitcnt lgkmcnt(7)
	v_mfma_f32_32x32x16_bf16 v[80:95], v[192:195], v[240:243], v[80:95]
	v_mfma_f32_32x32x16_bf16 v[16:31], v[220:223], v[240:243], v[16:31]
	ds_read_b128 v[240:243], v190 offset:46112
	ds_write_b128 v196, v[136:139]
	s_waitcnt lgkmcnt(8)
	v_mfma_f32_32x32x16_bf16 v[64:79], v[192:195], v[244:247], v[64:79]
	v_mfma_f32_32x32x16_bf16 v[0:15], v[220:223], v[244:247], v[0:15]
	ds_read_b128 v[244:247], v190 offset:50720
	ds_write_b128 v196, v[148:151] offset:36864
	ds_read_b128 v[192:195], v187 offset:64
	ds_read_b128 v[220:223], v187 offset:4672
	s_waitcnt lgkmcnt(9)
	v_mfma_f32_32x32x16_bf16 v[112:127], v[224:227], v[232:235], v[112:127]
	v_mfma_f32_32x32x16_bf16 v[48:63], v[228:231], v[232:235], v[48:63]
	ds_read_b128 v[232:235], v190 offset:36928
	ds_write_b128 v197, v[132:135]
	s_waitcnt lgkmcnt(9)
	v_mfma_f32_32x32x16_bf16 v[96:111], v[224:227], v[236:239], v[96:111]
	v_mfma_f32_32x32x16_bf16 v[32:47], v[228:231], v[236:239], v[32:47]
	ds_read_b128 v[236:239], v190 offset:41536
	ds_write_b128 v197, v[140:143] offset:36864
	s_waitcnt lgkmcnt(9)
	v_mfma_f32_32x32x16_bf16 v[80:95], v[224:227], v[240:243], v[80:95]
	v_mfma_f32_32x32x16_bf16 v[16:31], v[228:231], v[240:243], v[16:31]
	ds_read_b128 v[240:243], v190 offset:46144
	ds_write_b128 v249, v[128:131]
	s_waitcnt lgkmcnt(9)
	v_mfma_f32_32x32x16_bf16 v[64:79], v[224:227], v[244:247], v[64:79]
	v_mfma_f32_32x32x16_bf16 v[0:15], v[228:231], v[244:247], v[0:15]
	ds_read_b128 v[244:247], v190 offset:50752
	ds_write_b128 v249, v[156:159] offset:36864
	ds_read_b128 v[224:227], v187 offset:96
	ds_read_b128 v[228:231], v187 offset:4704
	s_waitcnt lgkmcnt(9)
	v_mfma_f32_32x32x16_bf16 v[112:127], v[192:195], v[232:235], v[112:127]
	v_mfma_f32_32x32x16_bf16 v[48:63], v[220:223], v[232:235], v[48:63]
	ds_read_b128 v[232:235], v190 offset:36960
	v_subrev_u32_e32 v191, 0x12000, v191
	s_waitcnt lgkmcnt(8)
	v_mfma_f32_32x32x16_bf16 v[96:111], v[192:195], v[236:239], v[96:111]
	v_mfma_f32_32x32x16_bf16 v[32:47], v[220:223], v[236:239], v[32:47]
	ds_read_b128 v[236:239], v190 offset:41568
	v_subrev_u32_e32 v196, 0x12000, v196
	s_waitcnt lgkmcnt(7)
	v_mfma_f32_32x32x16_bf16 v[80:95], v[192:195], v[240:243], v[80:95]
	v_mfma_f32_32x32x16_bf16 v[16:31], v[220:223], v[240:243], v[16:31]
	ds_read_b128 v[240:243], v190 offset:46176
	v_subrev_u32_e32 v197, 0x12000, v197
	s_waitcnt lgkmcnt(6)
	v_mfma_f32_32x32x16_bf16 v[64:79], v[192:195], v[244:247], v[64:79]
	v_mfma_f32_32x32x16_bf16 v[0:15], v[220:223], v[244:247], v[0:15]
	ds_read_b128 v[244:247], v190 offset:50784
	v_subrev_u32_e32 v249, 0x12000, v249
	v_add_u32_e32 v187, 0x12000, v187
	v_add_u32_e32 v190, 0x12000, v190
	s_waitcnt lgkmcnt(3)
	v_mfma_f32_32x32x16_bf16 v[112:127], v[224:227], v[232:235], v[112:127]
	v_mfma_f32_32x32x16_bf16 v[48:63], v[228:231], v[232:235], v[48:63]
	s_waitcnt lgkmcnt(2)
	v_mfma_f32_32x32x16_bf16 v[96:111], v[224:227], v[236:239], v[96:111]
	v_mfma_f32_32x32x16_bf16 v[32:47], v[228:231], v[236:239], v[32:47]
	s_waitcnt lgkmcnt(1)
	v_mfma_f32_32x32x16_bf16 v[80:95], v[224:227], v[240:243], v[80:95]
	v_mfma_f32_32x32x16_bf16 v[16:31], v[228:231], v[240:243], v[16:31]
	s_waitcnt lgkmcnt(0)
	v_mfma_f32_32x32x16_bf16 v[64:79], v[224:227], v[244:247], v[64:79]
	v_mfma_f32_32x32x16_bf16 v[0:15], v[228:231], v[244:247], v[0:15]
	s_waitcnt lgkmcnt(0)
	s_barrier
	ds_read_b128 v[192:195], v187 offset:0
	ds_read_b128 v[220:223], v187 offset:4608
	ds_read_b128 v[232:235], v190 offset:36864
	ds_read_b128 v[236:239], v190 offset:41472
	ds_read_b128 v[240:243], v190 offset:46080
	ds_read_b128 v[244:247], v190 offset:50688
	ds_read_b128 v[224:227], v187 offset:32
	ds_read_b128 v[228:231], v187 offset:4640
	s_waitcnt lgkmcnt(5)
	v_mfma_f32_32x32x16_bf16 v[112:127], v[192:195], v[232:235], v[112:127]
	v_mfma_f32_32x32x16_bf16 v[48:63], v[220:223], v[232:235], v[48:63]
	ds_read_b128 v[232:235], v190 offset:36896
	s_waitcnt lgkmcnt(5)
	v_mfma_f32_32x32x16_bf16 v[96:111], v[192:195], v[236:239], v[96:111]
	v_mfma_f32_32x32x16_bf16 v[32:47], v[220:223], v[236:239], v[32:47]
	ds_read_b128 v[236:239], v190 offset:41504
	s_waitcnt lgkmcnt(5)
	v_mfma_f32_32x32x16_bf16 v[80:95], v[192:195], v[240:243], v[80:95]
	v_mfma_f32_32x32x16_bf16 v[16:31], v[220:223], v[240:243], v[16:31]
	ds_read_b128 v[240:243], v190 offset:46112
	s_waitcnt lgkmcnt(5)
	v_mfma_f32_32x32x16_bf16 v[64:79], v[192:195], v[244:247], v[64:79]
	v_mfma_f32_32x32x16_bf16 v[0:15], v[220:223], v[244:247], v[0:15]
	ds_read_b128 v[244:247], v190 offset:50720
	ds_read_b128 v[192:195], v187 offset:64
	ds_read_b128 v[220:223], v187 offset:4672
	s_waitcnt lgkmcnt(5)
	v_mfma_f32_32x32x16_bf16 v[112:127], v[224:227], v[232:235], v[112:127]
	v_mfma_f32_32x32x16_bf16 v[48:63], v[228:231], v[232:235], v[48:63]
	ds_read_b128 v[232:235], v190 offset:36928
	s_waitcnt lgkmcnt(5)
; #define MFMA(a, b, c) __builtin_amdgcn_mfma_f32_32x32x16_bf16((a), (b), (c), 0, 0, 0)
; DI u16 f2bf(float a) { return (u16)(pack2(a, 0.f) & 0xffffu); }
; DI int crow(int reg, int g) { return (reg & 3) + 8 * (reg >> 2) + 4 * g; }
; DI float siluf(float x) { return x * __builtin_amdgcn_rcpf(1.f + __expf(-x)); }
; template <bool AT>
; DI void gemm_main(f32x16 (&acc)[2][4], const u16* __restrict__ R, int ldr, const u16* __restrict__ Cm, int ldc,
;                   const u16* __restrict__ RT, int ldrt, int K, char* smem, int tid) {
;     ...
;       for (int ks = 0; ks < 4; ++ks) {
;         bf16x8 rf[2];
; #pragma unroll
;         for (int rb = 0; rb < 2; ++rb) {
;           if (AT && kt < 8) {
;             const u16* src = RTs + (16 * ks + 8 * g) * 264 + 64 * wr + 32 * rb + li;
;             bf16x8 t;
; #pragma unroll
;             for (int j = 0; j < 8; ++j) t[j] = (short)src[j * 264];
;             rf[rb] = t;
;           } else {
;             rf[rb] = *(const bf16x8*)(Rs + (64 * wr + 32 * rb + li) * 72 + 16 * ks + 8 * g);
;           }
;         }
; #pragma unroll
;         for (int cb = 0; cb < 4; ++cb) {
;           const bf16x8 cfv = *(const bf16x8*)(Cs + (128 * wc + 32 * cb + li) * 72 + 16 * ks + 8 * g);
; #pragma unroll
;           for (int rb = 0; rb < 2; ++rb) acc[rb][cb] = MFMA(rf[rb], cfv, acc[rb][cb]);
;         }
;       }
;     }
;     __syncthreads();
; template <bool TR>
; DI void gemm_in_tile(const P& p, int l, int id, char* smem) {
;     ...
;   } else {
; #pragma unroll
;     for (int rb = 0; rb < 2; ++rb) {
; #pragma unroll
;       for (int reg = 0; reg < 16; ++reg) {
;         if ((reg & 7) == 0) asm volatile("" ::: "memory");
;         const int rl = 64 * wr + 32 * rb + crow(reg, g);
;         const int tok = m0 + rl;
;         const float rs = rs_s[rl];
; #pragma unroll
;         for (int cb = 0; cb < 4; ++cb) {
;           const int col = n0 - 3584 + 128 * wc + 32 * cb + li;
;           p.AG[(size_t)tok * 512 + col] = f2bf(siluf(acc[rb][cb][reg] * rs));
;         }
;       }
;     }
	v_mfma_f32_32x32x16_bf16 v[96:111], v[224:227], v[236:239], v[96:111]
	v_mfma_f32_32x32x16_bf16 v[32:47], v[228:231], v[236:239], v[32:47]
	ds_read_b128 v[236:239], v190 offset:41536
	s_waitcnt lgkmcnt(5)
	v_mfma_f32_32x32x16_bf16 v[80:95], v[224:227], v[240:243], v[80:95]
	v_mfma_f32_32x32x16_bf16 v[16:31], v[228:231], v[240:243], v[16:31]
	ds_read_b128 v[240:243], v190 offset:46144
	s_waitcnt lgkmcnt(5)
	v_mfma_f32_32x32x16_bf16 v[64:79], v[224:227], v[244:247], v[64:79]
	v_mfma_f32_32x32x16_bf16 v[0:15], v[228:231], v[244:247], v[0:15]
	ds_read_b128 v[244:247], v190 offset:50752
	ds_read_b128 v[224:227], v187 offset:96
	ds_read_b128 v[228:231], v187 offset:4704
	s_waitcnt lgkmcnt(5)
	v_mfma_f32_32x32x16_bf16 v[112:127], v[192:195], v[232:235], v[112:127]
	v_mfma_f32_32x32x16_bf16 v[48:63], v[220:223], v[232:235], v[48:63]
	ds_read_b128 v[232:235], v190 offset:36960
	v_add_u32_e32 v191, 0x12000, v191
	s_waitcnt lgkmcnt(5)
	v_mfma_f32_32x32x16_bf16 v[96:111], v[192:195], v[236:239], v[96:111]
	v_mfma_f32_32x32x16_bf16 v[32:47], v[220:223], v[236:239], v[32:47]
	ds_read_b128 v[236:239], v190 offset:41568
	v_add_u32_e32 v196, 0x12000, v196
	s_waitcnt lgkmcnt(5)
	v_mfma_f32_32x32x16_bf16 v[80:95], v[192:195], v[240:243], v[80:95]
	v_mfma_f32_32x32x16_bf16 v[16:31], v[220:223], v[240:243], v[16:31]
	ds_read_b128 v[240:243], v190 offset:46176
	v_add_u32_e32 v197, 0x12000, v197
	s_waitcnt lgkmcnt(5)
	v_mfma_f32_32x32x16_bf16 v[64:79], v[192:195], v[244:247], v[64:79]
	v_mfma_f32_32x32x16_bf16 v[0:15], v[220:223], v[244:247], v[0:15]
	ds_read_b128 v[244:247], v190 offset:50784
	v_add_u32_e32 v249, 0x12000, v249
	v_subrev_u32_e32 v187, 0x12000, v187
	v_subrev_u32_e32 v190, 0x12000, v190
	s_waitcnt lgkmcnt(3)
	v_mfma_f32_32x32x16_bf16 v[112:127], v[224:227], v[232:235], v[112:127]
	v_mfma_f32_32x32x16_bf16 v[48:63], v[228:231], v[232:235], v[48:63]
	s_waitcnt lgkmcnt(2)
	v_mfma_f32_32x32x16_bf16 v[96:111], v[224:227], v[236:239], v[96:111]
	v_mfma_f32_32x32x16_bf16 v[32:47], v[228:231], v[236:239], v[32:47]
	s_waitcnt lgkmcnt(1)
	v_mfma_f32_32x32x16_bf16 v[80:95], v[224:227], v[240:243], v[80:95]
	v_mfma_f32_32x32x16_bf16 v[16:31], v[228:231], v[240:243], v[16:31]
	s_waitcnt lgkmcnt(0)
	v_mfma_f32_32x32x16_bf16 v[64:79], v[224:227], v[244:247], v[64:79]
	v_mfma_f32_32x32x16_bf16 v[0:15], v[228:231], v[244:247], v[0:15]
	s_waitcnt lgkmcnt(0)
	s_barrier
	s_nop 7
	v_bfe_u32 v145, v176, 6, 1
	s_mov_b64 s[8:9], -1
	v_ashrrev_i32_e32 v140, 7, v176
	v_bfe_u32 v141, v176, 5, 1
	v_lshlrev_b32_e32 v128, 6, v140
	v_lshl_or_b32 v144, v141, 2, v128
	s_cmp_lt_u32 s11, 12
	s_cbranch_scc1 .LBB0_332
	s_add_i32 s8, s56, 0xfffff200
	v_lshlrev_b32_e32 v128, 7, v145
	v_or3_b32 v132, v128, s8, v177
	s_add_i32 s8, 0, 0x24000
	v_lshl_add_u32 v196, v144, 2, s8
	v_add_u32_e32 v140, s76, v144
	v_and_b32_e32 v251, 63, v198
	v_lshrrev_b32_e32 v133, 6, v198
	v_lshlrev_b32_e32 v133, 14, v133
	v_lshrrev_b32_e32 v134, 5, v251
	v_lshlrev_b32_e32 v134, 10, v134
	v_and_b32_e32 v135, 31, v251
	v_lshl_add_u32 v134, v135, 1, v134
	v_add_u32_e32 v197, v134, v133
	v_lshrrev_b32_e32 v134, 4, v251
	v_and_b32_e32 v135, 15, v251
	v_lshlrev_b32_e32 v136, 8, v134
	v_lshl_add_u32 v136, v135, 4, v136
	v_add_u32_e32 v249, v136, v133
	v_and_b32_e32 v140, 0xfffffffb, v140
	v_add_u32_e32 v140, v140, v134
	v_lshlrev_b32_e32 v140, 10, v140
	v_and_b32_e32 v132, 0xffffffe0, v132
	v_lshl_add_u32 v140, v132, 1, v140
	v_lshl_add_u32 v250, v135, 4, v140
	ds_read_b128 v[128:131], v196 offset:0
	s_waitcnt lgkmcnt(0)
	v_mul_f32_e32 v112, v112, v128
	v_mul_f32_e32 v96, v96, v128
	v_mul_f32_e32 v132, 0xbfb8aa3b, v112
	v_mul_f32_e32 v133, 0xbfb8aa3b, v96
	v_exp_f32_e32 v132, v132
	v_exp_f32_e32 v133, v133
	v_add_f32_e32 v132, 1.0, v132
	v_add_f32_e32 v133, 1.0, v133
	v_rcp_f32_e32 v132, v132
	v_rcp_f32_e32 v133, v133
	v_mul_f32_e32 v112, v112, v132
	v_mul_f32_e32 v96, v96, v133
	v_cvt_pk_bf16_f32 v134, v112, v96
	ds_write_b16 v197, v134 offset:0
	ds_write_b16_d16_hi v197, v134 offset:64
	v_mul_f32_e32 v80, v80, v128
	v_mul_f32_e32 v64, v64, v128
	v_mul_f32_e32 v136, 0xbfb8aa3b, v80
	v_mul_f32_e32 v137, 0xbfb8aa3b, v64
	v_exp_f32_e32 v136, v136
	v_exp_f32_e32 v137, v137
	v_add_f32_e32 v136, 1.0, v136
	v_add_f32_e32 v137, 1.0, v137
	v_rcp_f32_e32 v136, v136
	v_rcp_f32_e32 v137, v137
	v_mul_f32_e32 v80, v80, v136
	v_mul_f32_e32 v64, v64, v137
	v_cvt_pk_bf16_f32 v138, v80, v64
	ds_write_b16 v197, v138 offset:128
	ds_write_b16_d16_hi v197, v138 offset:192
	v_mul_f32_e32 v113, v113, v129
	v_mul_f32_e32 v97, v97, v129
	v_mul_f32_e32 v132, 0xbfb8aa3b, v113
	v_mul_f32_e32 v133, 0xbfb8aa3b, v97
	v_exp_f32_e32 v132, v132
	v_exp_f32_e32 v133, v133
	v_add_f32_e32 v132, 1.0, v132
	v_add_f32_e32 v133, 1.0, v133
	v_rcp_f32_e32 v132, v132
	v_rcp_f32_e32 v133, v133
	v_mul_f32_e32 v113, v113, v132
	v_mul_f32_e32 v97, v97, v133
	v_cvt_pk_bf16_f32 v134, v113, v97
	ds_write_b16 v197, v134 offset:256
	ds_write_b16_d16_hi v197, v134 offset:320
	v_mul_f32_e32 v81, v81, v129
	v_mul_f32_e32 v65, v65, v129
	v_mul_f32_e32 v136, 0xbfb8aa3b, v81
	v_mul_f32_e32 v137, 0xbfb8aa3b, v65
	v_exp_f32_e32 v136, v136
	v_exp_f32_e32 v137, v137
	v_add_f32_e32 v136, 1.0, v136
	v_add_f32_e32 v137, 1.0, v137
	v_rcp_f32_e32 v136, v136
	v_rcp_f32_e32 v137, v137
	v_mul_f32_e32 v81, v81, v136
	v_mul_f32_e32 v65, v65, v137
	v_cvt_pk_bf16_f32 v138, v81, v65
	ds_write_b16 v197, v138 offset:384
	ds_write_b16_d16_hi v197, v138 offset:448
	v_mul_f32_e32 v114, v114, v130
	v_mul_f32_e32 v98, v98, v130
	v_mul_f32_e32 v132, 0xbfb8aa3b, v114
	v_mul_f32_e32 v133, 0xbfb8aa3b, v98
	v_exp_f32_e32 v132, v132
	v_exp_f32_e32 v133, v133
	v_add_f32_e32 v132, 1.0, v132
; DI u16 f2bf(float a) { return (u16)(pack2(a, 0.f) & 0xffffu); }
; DI int crow(int reg, int g) { return (reg & 3) + 8 * (reg >> 2) + 4 * g; }
; DI float siluf(float x) { return x * __builtin_amdgcn_rcpf(1.f + __expf(-x)); }
; template <bool TR>
; DI void gemm_in_tile(const P& p, int l, int id, char* smem) {
;     ...
;   } else {
; #pragma unroll
;     for (int rb = 0; rb < 2; ++rb) {
; #pragma unroll
;       for (int reg = 0; reg < 16; ++reg) {
;         if ((reg & 7) == 0) asm volatile("" ::: "memory");
;         const int rl = 64 * wr + 32 * rb + crow(reg, g);
;         const int tok = m0 + rl;
;         const float rs = rs_s[rl];
; #pragma unroll
;         for (int cb = 0; cb < 4; ++cb) {
;           const int col = n0 - 3584 + 128 * wc + 32 * cb + li;
;           p.AG[(size_t)tok * 512 + col] = f2bf(siluf(acc[rb][cb][reg] * rs));
;         }
;       }
;     }
	v_add_f32_e32 v133, 1.0, v133
	v_rcp_f32_e32 v132, v132
	v_rcp_f32_e32 v133, v133
	v_mul_f32_e32 v114, v114, v132
	v_mul_f32_e32 v98, v98, v133
	v_cvt_pk_bf16_f32 v134, v114, v98
	ds_write_b16 v197, v134 offset:512
	ds_write_b16_d16_hi v197, v134 offset:576
	v_mul_f32_e32 v82, v82, v130
	v_mul_f32_e32 v66, v66, v130
	v_mul_f32_e32 v136, 0xbfb8aa3b, v82
	v_mul_f32_e32 v137, 0xbfb8aa3b, v66
	v_exp_f32_e32 v136, v136
	v_exp_f32_e32 v137, v137
	v_add_f32_e32 v136, 1.0, v136
	v_add_f32_e32 v137, 1.0, v137
	v_rcp_f32_e32 v136, v136
	v_rcp_f32_e32 v137, v137
	v_mul_f32_e32 v82, v82, v136
	v_mul_f32_e32 v66, v66, v137
	v_cvt_pk_bf16_f32 v138, v82, v66
	ds_write_b16 v197, v138 offset:640
	ds_write_b16_d16_hi v197, v138 offset:704
	v_mul_f32_e32 v115, v115, v131
	v_mul_f32_e32 v99, v99, v131
	v_mul_f32_e32 v132, 0xbfb8aa3b, v115
	v_mul_f32_e32 v133, 0xbfb8aa3b, v99
	v_exp_f32_e32 v132, v132
	v_exp_f32_e32 v133, v133
	v_add_f32_e32 v132, 1.0, v132
	v_add_f32_e32 v133, 1.0, v133
	v_rcp_f32_e32 v132, v132
	v_rcp_f32_e32 v133, v133
	v_mul_f32_e32 v115, v115, v132
	v_mul_f32_e32 v99, v99, v133
	v_cvt_pk_bf16_f32 v134, v115, v99
	ds_write_b16 v197, v134 offset:768
	ds_write_b16_d16_hi v197, v134 offset:832
	v_mul_f32_e32 v83, v83, v131
	v_mul_f32_e32 v67, v67, v131
	v_mul_f32_e32 v136, 0xbfb8aa3b, v83
	v_mul_f32_e32 v137, 0xbfb8aa3b, v67
	v_exp_f32_e32 v136, v136
	v_exp_f32_e32 v137, v137
	v_add_f32_e32 v136, 1.0, v136
	v_add_f32_e32 v137, 1.0, v137
	v_rcp_f32_e32 v136, v136
	v_rcp_f32_e32 v137, v137
	v_mul_f32_e32 v83, v83, v136
	v_mul_f32_e32 v67, v67, v137
	v_cvt_pk_bf16_f32 v138, v83, v67
	ds_write_b16 v197, v138 offset:896
	ds_write_b16_d16_hi v197, v138 offset:960
	ds_read_b128 v[128:131], v196 offset:32
	s_waitcnt lgkmcnt(0)
	v_mul_f32_e32 v116, v116, v128
	v_mul_f32_e32 v100, v100, v128
	v_mul_f32_e32 v132, 0xbfb8aa3b, v116
	v_mul_f32_e32 v133, 0xbfb8aa3b, v100
	v_exp_f32_e32 v132, v132
	v_exp_f32_e32 v133, v133
	v_add_f32_e32 v132, 1.0, v132
	v_add_f32_e32 v133, 1.0, v133
	v_rcp_f32_e32 v132, v132
	v_rcp_f32_e32 v133, v133
	v_mul_f32_e32 v116, v116, v132
	v_mul_f32_e32 v100, v100, v133
	v_cvt_pk_bf16_f32 v134, v116, v100
	ds_write_b16 v197, v134 offset:2048
	ds_write_b16_d16_hi v197, v134 offset:2112
	v_mul_f32_e32 v84, v84, v128
	v_mul_f32_e32 v68, v68, v128
	v_mul_f32_e32 v136, 0xbfb8aa3b, v84
	v_mul_f32_e32 v137, 0xbfb8aa3b, v68
	v_exp_f32_e32 v136, v136
	v_exp_f32_e32 v137, v137
	v_add_f32_e32 v136, 1.0, v136
	v_add_f32_e32 v137, 1.0, v137
	v_rcp_f32_e32 v136, v136
	v_rcp_f32_e32 v137, v137
	v_mul_f32_e32 v84, v84, v136
	v_mul_f32_e32 v68, v68, v137
	v_cvt_pk_bf16_f32 v138, v84, v68
	ds_write_b16 v197, v138 offset:2176
	ds_write_b16_d16_hi v197, v138 offset:2240
	v_mul_f32_e32 v117, v117, v129
	v_mul_f32_e32 v101, v101, v129
	v_mul_f32_e32 v132, 0xbfb8aa3b, v117
	v_mul_f32_e32 v133, 0xbfb8aa3b, v101
	v_exp_f32_e32 v132, v132
	v_exp_f32_e32 v133, v133
	v_add_f32_e32 v132, 1.0, v132
	v_add_f32_e32 v133, 1.0, v133
	v_rcp_f32_e32 v132, v132
	v_rcp_f32_e32 v133, v133
	v_mul_f32_e32 v117, v117, v132
	v_mul_f32_e32 v101, v101, v133
	v_cvt_pk_bf16_f32 v134, v117, v101
	ds_write_b16 v197, v134 offset:2304
	ds_write_b16_d16_hi v197, v134 offset:2368
	v_mul_f32_e32 v85, v85, v129
	v_mul_f32_e32 v69, v69, v129
	v_mul_f32_e32 v136, 0xbfb8aa3b, v85
	v_mul_f32_e32 v137, 0xbfb8aa3b, v69
	v_exp_f32_e32 v136, v136
	v_exp_f32_e32 v137, v137
	v_add_f32_e32 v136, 1.0, v136
	v_add_f32_e32 v137, 1.0, v137
	v_rcp_f32_e32 v136, v136
	v_rcp_f32_e32 v137, v137
	v_mul_f32_e32 v85, v85, v136
	v_mul_f32_e32 v69, v69, v137
	v_cvt_pk_bf16_f32 v138, v85, v69
	ds_write_b16 v197, v138 offset:2432
	ds_write_b16_d16_hi v197, v138 offset:2496
	v_mul_f32_e32 v118, v118, v130
	v_mul_f32_e32 v102, v102, v130
	v_mul_f32_e32 v132, 0xbfb8aa3b, v118
	v_mul_f32_e32 v133, 0xbfb8aa3b, v102
	v_exp_f32_e32 v132, v132
	v_exp_f32_e32 v133, v133
	v_add_f32_e32 v132, 1.0, v132
	v_add_f32_e32 v133, 1.0, v133
	v_rcp_f32_e32 v132, v132
	v_rcp_f32_e32 v133, v133
	v_mul_f32_e32 v118, v118, v132
	v_mul_f32_e32 v102, v102, v133
	v_cvt_pk_bf16_f32 v134, v118, v102
	ds_write_b16 v197, v134 offset:2560
	ds_write_b16_d16_hi v197, v134 offset:2624
	v_mul_f32_e32 v86, v86, v130
	v_mul_f32_e32 v70, v70, v130
	v_mul_f32_e32 v136, 0xbfb8aa3b, v86
	v_mul_f32_e32 v137, 0xbfb8aa3b, v70
	v_exp_f32_e32 v136, v136
	v_exp_f32_e32 v137, v137
	v_add_f32_e32 v136, 1.0, v136
	v_add_f32_e32 v137, 1.0, v137
	v_rcp_f32_e32 v136, v136
	v_rcp_f32_e32 v137, v137
	v_mul_f32_e32 v86, v86, v136
	v_mul_f32_e32 v70, v70, v137
	v_cvt_pk_bf16_f32 v138, v86, v70
	ds_write_b16 v197, v138 offset:2688
	ds_write_b16_d16_hi v197, v138 offset:2752
	v_mul_f32_e32 v119, v119, v131
	v_mul_f32_e32 v103, v103, v131
	v_mul_f32_e32 v132, 0xbfb8aa3b, v119
	v_mul_f32_e32 v133, 0xbfb8aa3b, v103
	v_exp_f32_e32 v132, v132
	v_exp_f32_e32 v133, v133
	v_add_f32_e32 v132, 1.0, v132
	v_add_f32_e32 v133, 1.0, v133
	v_rcp_f32_e32 v132, v132
	v_rcp_f32_e32 v133, v133
	v_mul_f32_e32 v119, v119, v132
	v_mul_f32_e32 v103, v103, v133
	v_cvt_pk_bf16_f32 v134, v119, v103
	ds_write_b16 v197, v134 offset:2816
	ds_write_b16_d16_hi v197, v134 offset:2880
	v_mul_f32_e32 v87, v87, v131
	v_mul_f32_e32 v71, v71, v131
	v_mul_f32_e32 v136, 0xbfb8aa3b, v87
	v_mul_f32_e32 v137, 0xbfb8aa3b, v71
	v_exp_f32_e32 v136, v136
	v_exp_f32_e32 v137, v137
	v_add_f32_e32 v136, 1.0, v136
	v_add_f32_e32 v137, 1.0, v137
	v_rcp_f32_e32 v136, v136
	v_rcp_f32_e32 v137, v137
	v_mul_f32_e32 v87, v87, v136
	v_mul_f32_e32 v71, v71, v137
	v_cvt_pk_bf16_f32 v138, v87, v71
	ds_write_b16 v197, v138 offset:2944
	ds_write_b16_d16_hi v197, v138 offset:3008
	ds_read_b128 v[128:131], v196 offset:64
	s_waitcnt lgkmcnt(0)
; DI u16 f2bf(float a) { return (u16)(pack2(a, 0.f) & 0xffffu); }
; DI int crow(int reg, int g) { return (reg & 3) + 8 * (reg >> 2) + 4 * g; }
; DI float siluf(float x) { return x * __builtin_amdgcn_rcpf(1.f + __expf(-x)); }
; template <bool TR>
; DI void gemm_in_tile(const P& p, int l, int id, char* smem) {
;     ...
;   } else {
; #pragma unroll
;     for (int rb = 0; rb < 2; ++rb) {
; #pragma unroll
;       for (int reg = 0; reg < 16; ++reg) {
;         if ((reg & 7) == 0) asm volatile("" ::: "memory");
;         const int rl = 64 * wr + 32 * rb + crow(reg, g);
;         const int tok = m0 + rl;
;         const float rs = rs_s[rl];
; #pragma unroll
;         for (int cb = 0; cb < 4; ++cb) {
;           const int col = n0 - 3584 + 128 * wc + 32 * cb + li;
;           p.AG[(size_t)tok * 512 + col] = f2bf(siluf(acc[rb][cb][reg] * rs));
;         }
;       }
;     }
	v_mul_f32_e32 v120, v120, v128
	v_mul_f32_e32 v104, v104, v128
	v_mul_f32_e32 v132, 0xbfb8aa3b, v120
	v_mul_f32_e32 v133, 0xbfb8aa3b, v104
	v_exp_f32_e32 v132, v132
	v_exp_f32_e32 v133, v133
	v_add_f32_e32 v132, 1.0, v132
	v_add_f32_e32 v133, 1.0, v133
	v_rcp_f32_e32 v132, v132
	v_rcp_f32_e32 v133, v133
	v_mul_f32_e32 v120, v120, v132
	v_mul_f32_e32 v104, v104, v133
	v_cvt_pk_bf16_f32 v134, v120, v104
	ds_write_b16 v197, v134 offset:4096
	ds_write_b16_d16_hi v197, v134 offset:4160
	v_mul_f32_e32 v88, v88, v128
	v_mul_f32_e32 v72, v72, v128
	v_mul_f32_e32 v136, 0xbfb8aa3b, v88
	v_mul_f32_e32 v137, 0xbfb8aa3b, v72
	v_exp_f32_e32 v136, v136
	v_exp_f32_e32 v137, v137
	v_add_f32_e32 v136, 1.0, v136
	v_add_f32_e32 v137, 1.0, v137
	v_rcp_f32_e32 v136, v136
	v_rcp_f32_e32 v137, v137
	v_mul_f32_e32 v88, v88, v136
	v_mul_f32_e32 v72, v72, v137
	v_cvt_pk_bf16_f32 v138, v88, v72
	ds_write_b16 v197, v138 offset:4224
	ds_write_b16_d16_hi v197, v138 offset:4288
	v_mul_f32_e32 v121, v121, v129
	v_mul_f32_e32 v105, v105, v129
	v_mul_f32_e32 v132, 0xbfb8aa3b, v121
	v_mul_f32_e32 v133, 0xbfb8aa3b, v105
	v_exp_f32_e32 v132, v132
	v_exp_f32_e32 v133, v133
	v_add_f32_e32 v132, 1.0, v132
	v_add_f32_e32 v133, 1.0, v133
	v_rcp_f32_e32 v132, v132
	v_rcp_f32_e32 v133, v133
	v_mul_f32_e32 v121, v121, v132
	v_mul_f32_e32 v105, v105, v133
	v_cvt_pk_bf16_f32 v134, v121, v105
	ds_write_b16 v197, v134 offset:4352
	ds_write_b16_d16_hi v197, v134 offset:4416
	v_mul_f32_e32 v89, v89, v129
	v_mul_f32_e32 v73, v73, v129
	v_mul_f32_e32 v136, 0xbfb8aa3b, v89
	v_mul_f32_e32 v137, 0xbfb8aa3b, v73
	v_exp_f32_e32 v136, v136
	v_exp_f32_e32 v137, v137
	v_add_f32_e32 v136, 1.0, v136
	v_add_f32_e32 v137, 1.0, v137
	v_rcp_f32_e32 v136, v136
	v_rcp_f32_e32 v137, v137
	v_mul_f32_e32 v89, v89, v136
	v_mul_f32_e32 v73, v73, v137
	v_cvt_pk_bf16_f32 v138, v89, v73
	ds_write_b16 v197, v138 offset:4480
	ds_write_b16_d16_hi v197, v138 offset:4544
	v_mul_f32_e32 v122, v122, v130
	v_mul_f32_e32 v106, v106, v130
	v_mul_f32_e32 v132, 0xbfb8aa3b, v122
	v_mul_f32_e32 v133, 0xbfb8aa3b, v106
	v_exp_f32_e32 v132, v132
	v_exp_f32_e32 v133, v133
	v_add_f32_e32 v132, 1.0, v132
	v_add_f32_e32 v133, 1.0, v133
	v_rcp_f32_e32 v132, v132
	v_rcp_f32_e32 v133, v133
	v_mul_f32_e32 v122, v122, v132
	v_mul_f32_e32 v106, v106, v133
	v_cvt_pk_bf16_f32 v134, v122, v106
	ds_write_b16 v197, v134 offset:4608
	ds_write_b16_d16_hi v197, v134 offset:4672
	v_mul_f32_e32 v90, v90, v130
	v_mul_f32_e32 v74, v74, v130
	v_mul_f32_e32 v136, 0xbfb8aa3b, v90
	v_mul_f32_e32 v137, 0xbfb8aa3b, v74
	v_exp_f32_e32 v136, v136
	v_exp_f32_e32 v137, v137
	v_add_f32_e32 v136, 1.0, v136
	v_add_f32_e32 v137, 1.0, v137
	v_rcp_f32_e32 v136, v136
	v_rcp_f32_e32 v137, v137
	v_mul_f32_e32 v90, v90, v136
	v_mul_f32_e32 v74, v74, v137
	v_cvt_pk_bf16_f32 v138, v90, v74
	ds_write_b16 v197, v138 offset:4736
	ds_write_b16_d16_hi v197, v138 offset:4800
	v_mul_f32_e32 v123, v123, v131
	v_mul_f32_e32 v107, v107, v131
	v_mul_f32_e32 v132, 0xbfb8aa3b, v123
	v_mul_f32_e32 v133, 0xbfb8aa3b, v107
	v_exp_f32_e32 v132, v132
	v_exp_f32_e32 v133, v133
	v_add_f32_e32 v132, 1.0, v132
	v_add_f32_e32 v133, 1.0, v133
	v_rcp_f32_e32 v132, v132
	v_rcp_f32_e32 v133, v133
	v_mul_f32_e32 v123, v123, v132
	v_mul_f32_e32 v107, v107, v133
	v_cvt_pk_bf16_f32 v134, v123, v107
	ds_write_b16 v197, v134 offset:4864
	ds_write_b16_d16_hi v197, v134 offset:4928
	v_mul_f32_e32 v91, v91, v131
	v_mul_f32_e32 v75, v75, v131
	v_mul_f32_e32 v136, 0xbfb8aa3b, v91
	v_mul_f32_e32 v137, 0xbfb8aa3b, v75
	v_exp_f32_e32 v136, v136
	v_exp_f32_e32 v137, v137
	v_add_f32_e32 v136, 1.0, v136
	v_add_f32_e32 v137, 1.0, v137
	v_rcp_f32_e32 v136, v136
	v_rcp_f32_e32 v137, v137
	v_mul_f32_e32 v91, v91, v136
	v_mul_f32_e32 v75, v75, v137
	v_cvt_pk_bf16_f32 v138, v91, v75
	ds_write_b16 v197, v138 offset:4992
	ds_write_b16_d16_hi v197, v138 offset:5056
	ds_read_b128 v[128:131], v196 offset:96
	s_waitcnt lgkmcnt(0)
	v_mul_f32_e32 v124, v124, v128
	v_mul_f32_e32 v108, v108, v128
	v_mul_f32_e32 v132, 0xbfb8aa3b, v124
	v_mul_f32_e32 v133, 0xbfb8aa3b, v108
	v_exp_f32_e32 v132, v132
	v_exp_f32_e32 v133, v133
	v_add_f32_e32 v132, 1.0, v132
	v_add_f32_e32 v133, 1.0, v133
	v_rcp_f32_e32 v132, v132
	v_rcp_f32_e32 v133, v133
	v_mul_f32_e32 v124, v124, v132
	v_mul_f32_e32 v108, v108, v133
	v_cvt_pk_bf16_f32 v134, v124, v108
	ds_write_b16 v197, v134 offset:6144
	ds_write_b16_d16_hi v197, v134 offset:6208
	v_mul_f32_e32 v92, v92, v128
	v_mul_f32_e32 v76, v76, v128
	v_mul_f32_e32 v136, 0xbfb8aa3b, v92
	v_mul_f32_e32 v137, 0xbfb8aa3b, v76
	v_exp_f32_e32 v136, v136
	v_exp_f32_e32 v137, v137
	v_add_f32_e32 v136, 1.0, v136
	v_add_f32_e32 v137, 1.0, v137
	v_rcp_f32_e32 v136, v136
	v_rcp_f32_e32 v137, v137
	v_mul_f32_e32 v92, v92, v136
	v_mul_f32_e32 v76, v76, v137
	v_cvt_pk_bf16_f32 v138, v92, v76
	ds_write_b16 v197, v138 offset:6272
	ds_write_b16_d16_hi v197, v138 offset:6336
	v_mul_f32_e32 v125, v125, v129
	v_mul_f32_e32 v109, v109, v129
	v_mul_f32_e32 v132, 0xbfb8aa3b, v125
	v_mul_f32_e32 v133, 0xbfb8aa3b, v109
	v_exp_f32_e32 v132, v132
	v_exp_f32_e32 v133, v133
	v_add_f32_e32 v132, 1.0, v132
	v_add_f32_e32 v133, 1.0, v133
	v_rcp_f32_e32 v132, v132
	v_rcp_f32_e32 v133, v133
	v_mul_f32_e32 v125, v125, v132
	v_mul_f32_e32 v109, v109, v133
	v_cvt_pk_bf16_f32 v134, v125, v109
	ds_write_b16 v197, v134 offset:6400
	ds_write_b16_d16_hi v197, v134 offset:6464
	v_mul_f32_e32 v93, v93, v129
	v_mul_f32_e32 v77, v77, v129
	v_mul_f32_e32 v136, 0xbfb8aa3b, v93
	v_mul_f32_e32 v137, 0xbfb8aa3b, v77
	v_exp_f32_e32 v136, v136
	v_exp_f32_e32 v137, v137
	v_add_f32_e32 v136, 1.0, v136
	v_add_f32_e32 v137, 1.0, v137
	v_rcp_f32_e32 v136, v136
; DI u16 f2bf(float a) { return (u16)(pack2(a, 0.f) & 0xffffu); }
; DI int crow(int reg, int g) { return (reg & 3) + 8 * (reg >> 2) + 4 * g; }
; DI float siluf(float x) { return x * __builtin_amdgcn_rcpf(1.f + __expf(-x)); }
; template <bool TR>
; DI void gemm_in_tile(const P& p, int l, int id, char* smem) {
;     ...
;   } else {
; #pragma unroll
;     for (int rb = 0; rb < 2; ++rb) {
; #pragma unroll
;       for (int reg = 0; reg < 16; ++reg) {
;         if ((reg & 7) == 0) asm volatile("" ::: "memory");
;         const int rl = 64 * wr + 32 * rb + crow(reg, g);
;         const int tok = m0 + rl;
;         const float rs = rs_s[rl];
; #pragma unroll
;         for (int cb = 0; cb < 4; ++cb) {
;           const int col = n0 - 3584 + 128 * wc + 32 * cb + li;
;           p.AG[(size_t)tok * 512 + col] = f2bf(siluf(acc[rb][cb][reg] * rs));
;         }
;       }
;     }
	v_rcp_f32_e32 v137, v137
	v_mul_f32_e32 v93, v93, v136
	v_mul_f32_e32 v77, v77, v137
	v_cvt_pk_bf16_f32 v138, v93, v77
	ds_write_b16 v197, v138 offset:6528
	ds_write_b16_d16_hi v197, v138 offset:6592
	v_mul_f32_e32 v126, v126, v130
	v_mul_f32_e32 v110, v110, v130
	v_mul_f32_e32 v132, 0xbfb8aa3b, v126
	v_mul_f32_e32 v133, 0xbfb8aa3b, v110
	v_exp_f32_e32 v132, v132
	v_exp_f32_e32 v133, v133
	v_add_f32_e32 v132, 1.0, v132
	v_add_f32_e32 v133, 1.0, v133
	v_rcp_f32_e32 v132, v132
	v_rcp_f32_e32 v133, v133
	v_mul_f32_e32 v126, v126, v132
	v_mul_f32_e32 v110, v110, v133
	v_cvt_pk_bf16_f32 v134, v126, v110
	ds_write_b16 v197, v134 offset:6656
	ds_write_b16_d16_hi v197, v134 offset:6720
	v_mul_f32_e32 v94, v94, v130
	v_mul_f32_e32 v78, v78, v130
	v_mul_f32_e32 v136, 0xbfb8aa3b, v94
	v_mul_f32_e32 v137, 0xbfb8aa3b, v78
	v_exp_f32_e32 v136, v136
	v_exp_f32_e32 v137, v137
	v_add_f32_e32 v136, 1.0, v136
	v_add_f32_e32 v137, 1.0, v137
	v_rcp_f32_e32 v136, v136
	v_rcp_f32_e32 v137, v137
	v_mul_f32_e32 v94, v94, v136
	v_mul_f32_e32 v78, v78, v137
	v_cvt_pk_bf16_f32 v138, v94, v78
	ds_write_b16 v197, v138 offset:6784
	ds_write_b16_d16_hi v197, v138 offset:6848
	v_mul_f32_e32 v127, v127, v131
	v_mul_f32_e32 v111, v111, v131
	v_mul_f32_e32 v132, 0xbfb8aa3b, v127
	v_mul_f32_e32 v133, 0xbfb8aa3b, v111
	v_exp_f32_e32 v132, v132
	v_exp_f32_e32 v133, v133
	v_add_f32_e32 v132, 1.0, v132
	v_add_f32_e32 v133, 1.0, v133
	v_rcp_f32_e32 v132, v132
	v_rcp_f32_e32 v133, v133
	v_mul_f32_e32 v127, v127, v132
	v_mul_f32_e32 v111, v111, v133
	v_cvt_pk_bf16_f32 v134, v127, v111
	ds_write_b16 v197, v134 offset:6912
	ds_write_b16_d16_hi v197, v134 offset:6976
	v_mul_f32_e32 v95, v95, v131
	v_mul_f32_e32 v79, v79, v131
	v_mul_f32_e32 v136, 0xbfb8aa3b, v95
	v_mul_f32_e32 v137, 0xbfb8aa3b, v79
	v_exp_f32_e32 v136, v136
	v_exp_f32_e32 v137, v137
	v_add_f32_e32 v136, 1.0, v136
	v_add_f32_e32 v137, 1.0, v137
	v_rcp_f32_e32 v136, v136
	v_rcp_f32_e32 v137, v137
	v_mul_f32_e32 v95, v95, v136
	v_mul_f32_e32 v79, v79, v137
	v_cvt_pk_bf16_f32 v138, v95, v79
	ds_write_b16 v197, v138 offset:7040
	ds_write_b16_d16_hi v197, v138 offset:7104
	ds_read_b128 v[128:131], v196 offset:128
	s_waitcnt lgkmcnt(0)
	v_mul_f32_e32 v48, v48, v128
	v_mul_f32_e32 v32, v32, v128
	v_mul_f32_e32 v132, 0xbfb8aa3b, v48
	v_mul_f32_e32 v133, 0xbfb8aa3b, v32
	v_exp_f32_e32 v132, v132
	v_exp_f32_e32 v133, v133
	v_add_f32_e32 v132, 1.0, v132
	v_add_f32_e32 v133, 1.0, v133
	v_rcp_f32_e32 v132, v132
	v_rcp_f32_e32 v133, v133
	v_mul_f32_e32 v48, v48, v132
	v_mul_f32_e32 v32, v32, v133
	v_cvt_pk_bf16_f32 v134, v48, v32
	ds_write_b16 v197, v134 offset:8192
	ds_write_b16_d16_hi v197, v134 offset:8256
	v_mul_f32_e32 v16, v16, v128
	v_mul_f32_e32 v0, v0, v128
	v_mul_f32_e32 v136, 0xbfb8aa3b, v16
	v_mul_f32_e32 v137, 0xbfb8aa3b, v0
	v_exp_f32_e32 v136, v136
	v_exp_f32_e32 v137, v137
	v_add_f32_e32 v136, 1.0, v136
	v_add_f32_e32 v137, 1.0, v137
	v_rcp_f32_e32 v136, v136
	v_rcp_f32_e32 v137, v137
	v_mul_f32_e32 v16, v16, v136
	v_mul_f32_e32 v0, v0, v137
	v_cvt_pk_bf16_f32 v138, v16, v0
	ds_write_b16 v197, v138 offset:8320
	ds_write_b16_d16_hi v197, v138 offset:8384
	v_mul_f32_e32 v49, v49, v129
	v_mul_f32_e32 v33, v33, v129
	v_mul_f32_e32 v132, 0xbfb8aa3b, v49
	v_mul_f32_e32 v133, 0xbfb8aa3b, v33
	v_exp_f32_e32 v132, v132
	v_exp_f32_e32 v133, v133
	v_add_f32_e32 v132, 1.0, v132
	v_add_f32_e32 v133, 1.0, v133
	v_rcp_f32_e32 v132, v132
	v_rcp_f32_e32 v133, v133
	v_mul_f32_e32 v49, v49, v132
	v_mul_f32_e32 v33, v33, v133
	v_cvt_pk_bf16_f32 v134, v49, v33
	ds_write_b16 v197, v134 offset:8448
	ds_write_b16_d16_hi v197, v134 offset:8512
	v_mul_f32_e32 v17, v17, v129
	v_mul_f32_e32 v1, v1, v129
	v_mul_f32_e32 v136, 0xbfb8aa3b, v17
	v_mul_f32_e32 v137, 0xbfb8aa3b, v1
	v_exp_f32_e32 v136, v136
	v_exp_f32_e32 v137, v137
	v_add_f32_e32 v136, 1.0, v136
	v_add_f32_e32 v137, 1.0, v137
	v_rcp_f32_e32 v136, v136
	v_rcp_f32_e32 v137, v137
	v_mul_f32_e32 v17, v17, v136
	v_mul_f32_e32 v1, v1, v137
	v_cvt_pk_bf16_f32 v138, v17, v1
	ds_write_b16 v197, v138 offset:8576
	ds_write_b16_d16_hi v197, v138 offset:8640
	v_mul_f32_e32 v50, v50, v130
	v_mul_f32_e32 v34, v34, v130
	v_mul_f32_e32 v132, 0xbfb8aa3b, v50
	v_mul_f32_e32 v133, 0xbfb8aa3b, v34
	v_exp_f32_e32 v132, v132
	v_exp_f32_e32 v133, v133
	v_add_f32_e32 v132, 1.0, v132
	v_add_f32_e32 v133, 1.0, v133
	v_rcp_f32_e32 v132, v132
	v_rcp_f32_e32 v133, v133
	v_mul_f32_e32 v50, v50, v132
	v_mul_f32_e32 v34, v34, v133
	v_cvt_pk_bf16_f32 v134, v50, v34
	ds_write_b16 v197, v134 offset:8704
	ds_write_b16_d16_hi v197, v134 offset:8768
	v_mul_f32_e32 v18, v18, v130
	v_mul_f32_e32 v2, v2, v130
	v_mul_f32_e32 v136, 0xbfb8aa3b, v18
	v_mul_f32_e32 v137, 0xbfb8aa3b, v2
	v_exp_f32_e32 v136, v136
	v_exp_f32_e32 v137, v137
	v_add_f32_e32 v136, 1.0, v136
	v_add_f32_e32 v137, 1.0, v137
	v_rcp_f32_e32 v136, v136
	v_rcp_f32_e32 v137, v137
	v_mul_f32_e32 v18, v18, v136
	v_mul_f32_e32 v2, v2, v137
	v_cvt_pk_bf16_f32 v138, v18, v2
	ds_write_b16 v197, v138 offset:8832
	ds_write_b16_d16_hi v197, v138 offset:8896
	v_mul_f32_e32 v51, v51, v131
	v_mul_f32_e32 v35, v35, v131
	v_mul_f32_e32 v132, 0xbfb8aa3b, v51
	v_mul_f32_e32 v133, 0xbfb8aa3b, v35
	v_exp_f32_e32 v132, v132
	v_exp_f32_e32 v133, v133
	v_add_f32_e32 v132, 1.0, v132
	v_add_f32_e32 v133, 1.0, v133
	v_rcp_f32_e32 v132, v132
	v_rcp_f32_e32 v133, v133
	v_mul_f32_e32 v51, v51, v132
	v_mul_f32_e32 v35, v35, v133
	v_cvt_pk_bf16_f32 v134, v51, v35
	ds_write_b16 v197, v134 offset:8960
	ds_write_b16_d16_hi v197, v134 offset:9024
	v_mul_f32_e32 v19, v19, v131
	v_mul_f32_e32 v3, v3, v131
	v_mul_f32_e32 v136, 0xbfb8aa3b, v19
	v_mul_f32_e32 v137, 0xbfb8aa3b, v3
	v_exp_f32_e32 v136, v136
	v_exp_f32_e32 v137, v137
	v_add_f32_e32 v136, 1.0, v136
	v_add_f32_e32 v137, 1.0, v137
	v_rcp_f32_e32 v136, v136
	v_rcp_f32_e32 v137, v137
	v_mul_f32_e32 v19, v19, v136
	v_mul_f32_e32 v3, v3, v137
	v_cvt_pk_bf16_f32 v138, v19, v3
	ds_write_b16 v197, v138 offset:9088
	ds_write_b16_d16_hi v197, v138 offset:9152
	ds_read_b128 v[128:131], v196 offset:160
	s_waitcnt lgkmcnt(0)
; DI u16 f2bf(float a) { return (u16)(pack2(a, 0.f) & 0xffffu); }
; DI int crow(int reg, int g) { return (reg & 3) + 8 * (reg >> 2) + 4 * g; }
; DI float siluf(float x) { return x * __builtin_amdgcn_rcpf(1.f + __expf(-x)); }
; template <bool TR>
; DI void gemm_in_tile(const P& p, int l, int id, char* smem) {
;     ...
; #pragma unroll
;     for (int rb = 0; rb < 2; ++rb) {
; #pragma unroll
;       for (int reg = 0; reg < 16; ++reg) {
;         if ((reg & 7) == 0) asm volatile("" ::: "memory");
;         const int rl = 64 * wr + 32 * rb + crow(reg, g);
;         const int tok = m0 + rl;
;         const float rs = rs_s[rl];
; #pragma unroll
;         for (int cb = 0; cb < 4; ++cb) {
;           const int col = n0 - 3584 + 128 * wc + 32 * cb + li;
;           p.AG[(size_t)tok * 512 + col] = f2bf(siluf(acc[rb][cb][reg] * rs));
;         }
;       }
;     }
	v_mul_f32_e32 v52, v52, v128
	v_mul_f32_e32 v36, v36, v128
	v_mul_f32_e32 v132, 0xbfb8aa3b, v52
	v_mul_f32_e32 v133, 0xbfb8aa3b, v36
	v_exp_f32_e32 v132, v132
	v_exp_f32_e32 v133, v133
	v_add_f32_e32 v132, 1.0, v132
	v_add_f32_e32 v133, 1.0, v133
	v_rcp_f32_e32 v132, v132
	v_rcp_f32_e32 v133, v133
	v_mul_f32_e32 v52, v52, v132
	v_mul_f32_e32 v36, v36, v133
	v_cvt_pk_bf16_f32 v134, v52, v36
	ds_write_b16 v197, v134 offset:10240
	ds_write_b16_d16_hi v197, v134 offset:10304
	v_mul_f32_e32 v20, v20, v128
	v_mul_f32_e32 v4, v4, v128
	v_mul_f32_e32 v136, 0xbfb8aa3b, v20
	v_mul_f32_e32 v137, 0xbfb8aa3b, v4
	v_exp_f32_e32 v136, v136
	v_exp_f32_e32 v137, v137
	v_add_f32_e32 v136, 1.0, v136
	v_add_f32_e32 v137, 1.0, v137
	v_rcp_f32_e32 v136, v136
	v_rcp_f32_e32 v137, v137
	v_mul_f32_e32 v20, v20, v136
	v_mul_f32_e32 v4, v4, v137
	v_cvt_pk_bf16_f32 v138, v20, v4
	ds_write_b16 v197, v138 offset:10368
	ds_write_b16_d16_hi v197, v138 offset:10432
	v_mul_f32_e32 v53, v53, v129
	v_mul_f32_e32 v37, v37, v129
	v_mul_f32_e32 v132, 0xbfb8aa3b, v53
	v_mul_f32_e32 v133, 0xbfb8aa3b, v37
	v_exp_f32_e32 v132, v132
	v_exp_f32_e32 v133, v133
	v_add_f32_e32 v132, 1.0, v132
	v_add_f32_e32 v133, 1.0, v133
	v_rcp_f32_e32 v132, v132
	v_rcp_f32_e32 v133, v133
	v_mul_f32_e32 v53, v53, v132
	v_mul_f32_e32 v37, v37, v133
	v_cvt_pk_bf16_f32 v134, v53, v37
	ds_write_b16 v197, v134 offset:10496
	ds_write_b16_d16_hi v197, v134 offset:10560
	v_mul_f32_e32 v21, v21, v129
	v_mul_f32_e32 v5, v5, v129
	v_mul_f32_e32 v136, 0xbfb8aa3b, v21
	v_mul_f32_e32 v137, 0xbfb8aa3b, v5
	v_exp_f32_e32 v136, v136
	v_exp_f32_e32 v137, v137
	v_add_f32_e32 v136, 1.0, v136
	v_add_f32_e32 v137, 1.0, v137
	v_rcp_f32_e32 v136, v136
	v_rcp_f32_e32 v137, v137
	v_mul_f32_e32 v21, v21, v136
	v_mul_f32_e32 v5, v5, v137
	v_cvt_pk_bf16_f32 v138, v21, v5
	ds_write_b16 v197, v138 offset:10624
	ds_write_b16_d16_hi v197, v138 offset:10688
	v_mul_f32_e32 v54, v54, v130
	v_mul_f32_e32 v38, v38, v130
	v_mul_f32_e32 v132, 0xbfb8aa3b, v54
	v_mul_f32_e32 v133, 0xbfb8aa3b, v38
	v_exp_f32_e32 v132, v132
	v_exp_f32_e32 v133, v133
	v_add_f32_e32 v132, 1.0, v132
	v_add_f32_e32 v133, 1.0, v133
	v_rcp_f32_e32 v132, v132
	v_rcp_f32_e32 v133, v133
	v_mul_f32_e32 v54, v54, v132
	v_mul_f32_e32 v38, v38, v133
	v_cvt_pk_bf16_f32 v134, v54, v38
	ds_write_b16 v197, v134 offset:10752
	ds_write_b16_d16_hi v197, v134 offset:10816
	v_mul_f32_e32 v22, v22, v130
	v_mul_f32_e32 v6, v6, v130
	v_mul_f32_e32 v136, 0xbfb8aa3b, v22
	v_mul_f32_e32 v137, 0xbfb8aa3b, v6
	v_exp_f32_e32 v136, v136
	v_exp_f32_e32 v137, v137
	v_add_f32_e32 v136, 1.0, v136
	v_add_f32_e32 v137, 1.0, v137
	v_rcp_f32_e32 v136, v136
	v_rcp_f32_e32 v137, v137
	v_mul_f32_e32 v22, v22, v136
	v_mul_f32_e32 v6, v6, v137
	v_cvt_pk_bf16_f32 v138, v22, v6
	ds_write_b16 v197, v138 offset:10880
	ds_write_b16_d16_hi v197, v138 offset:10944
	v_mul_f32_e32 v55, v55, v131
	v_mul_f32_e32 v39, v39, v131
	v_mul_f32_e32 v132, 0xbfb8aa3b, v55
	v_mul_f32_e32 v133, 0xbfb8aa3b, v39
	v_exp_f32_e32 v132, v132
	v_exp_f32_e32 v133, v133
	v_add_f32_e32 v132, 1.0, v132
	v_add_f32_e32 v133, 1.0, v133
	v_rcp_f32_e32 v132, v132
	v_rcp_f32_e32 v133, v133
	v_mul_f32_e32 v55, v55, v132
	v_mul_f32_e32 v39, v39, v133
	v_cvt_pk_bf16_f32 v134, v55, v39
	ds_write_b16 v197, v134 offset:11008
	ds_write_b16_d16_hi v197, v134 offset:11072
	v_mul_f32_e32 v23, v23, v131
	v_mul_f32_e32 v7, v7, v131
	v_mul_f32_e32 v136, 0xbfb8aa3b, v23
	v_mul_f32_e32 v137, 0xbfb8aa3b, v7
	v_exp_f32_e32 v136, v136
	v_exp_f32_e32 v137, v137
	v_add_f32_e32 v136, 1.0, v136
	v_add_f32_e32 v137, 1.0, v137
	v_rcp_f32_e32 v136, v136
	v_rcp_f32_e32 v137, v137
	v_mul_f32_e32 v23, v23, v136
	v_mul_f32_e32 v7, v7, v137
	v_cvt_pk_bf16_f32 v138, v23, v7
	ds_write_b16 v197, v138 offset:11136
	ds_write_b16_d16_hi v197, v138 offset:11200
	ds_read_b128 v[128:131], v196 offset:192
	s_waitcnt lgkmcnt(0)
	v_mul_f32_e32 v56, v56, v128
	v_mul_f32_e32 v40, v40, v128
	v_mul_f32_e32 v132, 0xbfb8aa3b, v56
	v_mul_f32_e32 v133, 0xbfb8aa3b, v40
	v_exp_f32_e32 v132, v132
	v_exp_f32_e32 v133, v133
	v_add_f32_e32 v132, 1.0, v132
	v_add_f32_e32 v133, 1.0, v133
	v_rcp_f32_e32 v132, v132
	v_rcp_f32_e32 v133, v133
	v_mul_f32_e32 v56, v56, v132
	v_mul_f32_e32 v40, v40, v133
	v_cvt_pk_bf16_f32 v134, v56, v40
	ds_write_b16 v197, v134 offset:12288
	ds_write_b16_d16_hi v197, v134 offset:12352
	v_mul_f32_e32 v24, v24, v128
	v_mul_f32_e32 v8, v8, v128
	v_mul_f32_e32 v136, 0xbfb8aa3b, v24
	v_mul_f32_e32 v137, 0xbfb8aa3b, v8
	v_exp_f32_e32 v136, v136
	v_exp_f32_e32 v137, v137
	v_add_f32_e32 v136, 1.0, v136
	v_add_f32_e32 v137, 1.0, v137
	v_rcp_f32_e32 v136, v136
	v_rcp_f32_e32 v137, v137
	v_mul_f32_e32 v24, v24, v136
	v_mul_f32_e32 v8, v8, v137
	v_cvt_pk_bf16_f32 v138, v24, v8
	ds_write_b16 v197, v138 offset:12416
	ds_write_b16_d16_hi v197, v138 offset:12480
	v_mul_f32_e32 v57, v57, v129
	v_mul_f32_e32 v41, v41, v129
	v_mul_f32_e32 v132, 0xbfb8aa3b, v57
	v_mul_f32_e32 v133, 0xbfb8aa3b, v41
	v_exp_f32_e32 v132, v132
	v_exp_f32_e32 v133, v133
	v_add_f32_e32 v132, 1.0, v132
	v_add_f32_e32 v133, 1.0, v133
	v_rcp_f32_e32 v132, v132
	v_rcp_f32_e32 v133, v133
	v_mul_f32_e32 v57, v57, v132
	v_mul_f32_e32 v41, v41, v133
	v_cvt_pk_bf16_f32 v134, v57, v41
	ds_write_b16 v197, v134 offset:12544
	ds_write_b16_d16_hi v197, v134 offset:12608
	v_mul_f32_e32 v25, v25, v129
	v_mul_f32_e32 v9, v9, v129
	v_mul_f32_e32 v136, 0xbfb8aa3b, v25
	v_mul_f32_e32 v137, 0xbfb8aa3b, v9
	v_exp_f32_e32 v136, v136
	v_exp_f32_e32 v137, v137
	v_add_f32_e32 v136, 1.0, v136
	v_add_f32_e32 v137, 1.0, v137
	v_rcp_f32_e32 v136, v136
	v_rcp_f32_e32 v137, v137
	v_mul_f32_e32 v25, v25, v136
	v_mul_f32_e32 v9, v9, v137
; DI u16 f2bf(float a) { return (u16)(pack2(a, 0.f) & 0xffffu); }
; DI int crow(int reg, int g) { return (reg & 3) + 8 * (reg >> 2) + 4 * g; }
; DI float siluf(float x) { return x * __builtin_amdgcn_rcpf(1.f + __expf(-x)); }
; template <bool TR>
; DI void gemm_in_tile(const P& p, int l, int id, char* smem) {
;     ...
; #pragma unroll
;     for (int rb = 0; rb < 2; ++rb) {
; #pragma unroll
;       for (int reg = 0; reg < 16; ++reg) {
;         if ((reg & 7) == 0) asm volatile("" ::: "memory");
;         const int rl = 64 * wr + 32 * rb + crow(reg, g);
;         const int tok = m0 + rl;
;         const float rs = rs_s[rl];
; #pragma unroll
;         for (int cb = 0; cb < 4; ++cb) {
;           const int col = n0 - 3584 + 128 * wc + 32 * cb + li;
;           p.AG[(size_t)tok * 512 + col] = f2bf(siluf(acc[rb][cb][reg] * rs));
;         }
;       }
;     }
	v_cvt_pk_bf16_f32 v138, v25, v9
	ds_write_b16 v197, v138 offset:12672
	ds_write_b16_d16_hi v197, v138 offset:12736
	v_mul_f32_e32 v58, v58, v130
	v_mul_f32_e32 v42, v42, v130
	v_mul_f32_e32 v132, 0xbfb8aa3b, v58
	v_mul_f32_e32 v133, 0xbfb8aa3b, v42
	v_exp_f32_e32 v132, v132
	v_exp_f32_e32 v133, v133
	v_add_f32_e32 v132, 1.0, v132
	v_add_f32_e32 v133, 1.0, v133
	v_rcp_f32_e32 v132, v132
	v_rcp_f32_e32 v133, v133
	v_mul_f32_e32 v58, v58, v132
	v_mul_f32_e32 v42, v42, v133
	v_cvt_pk_bf16_f32 v134, v58, v42
	ds_write_b16 v197, v134 offset:12800
	ds_write_b16_d16_hi v197, v134 offset:12864
	v_mul_f32_e32 v26, v26, v130
	v_mul_f32_e32 v10, v10, v130
	v_mul_f32_e32 v136, 0xbfb8aa3b, v26
	v_mul_f32_e32 v137, 0xbfb8aa3b, v10
	v_exp_f32_e32 v136, v136
	v_exp_f32_e32 v137, v137
	v_add_f32_e32 v136, 1.0, v136
	v_add_f32_e32 v137, 1.0, v137
	v_rcp_f32_e32 v136, v136
	v_rcp_f32_e32 v137, v137
	v_mul_f32_e32 v26, v26, v136
	v_mul_f32_e32 v10, v10, v137
	v_cvt_pk_bf16_f32 v138, v26, v10
	ds_write_b16 v197, v138 offset:12928
	ds_write_b16_d16_hi v197, v138 offset:12992
	v_mul_f32_e32 v59, v59, v131
	v_mul_f32_e32 v43, v43, v131
	v_mul_f32_e32 v132, 0xbfb8aa3b, v59
	v_mul_f32_e32 v133, 0xbfb8aa3b, v43
	v_exp_f32_e32 v132, v132
	v_exp_f32_e32 v133, v133
	v_add_f32_e32 v132, 1.0, v132
	v_add_f32_e32 v133, 1.0, v133
	v_rcp_f32_e32 v132, v132
	v_rcp_f32_e32 v133, v133
	v_mul_f32_e32 v59, v59, v132
	v_mul_f32_e32 v43, v43, v133
	v_cvt_pk_bf16_f32 v134, v59, v43
	ds_write_b16 v197, v134 offset:13056
	ds_write_b16_d16_hi v197, v134 offset:13120
	v_mul_f32_e32 v27, v27, v131
	v_mul_f32_e32 v11, v11, v131
	v_mul_f32_e32 v136, 0xbfb8aa3b, v27
	v_mul_f32_e32 v137, 0xbfb8aa3b, v11
	v_exp_f32_e32 v136, v136
	v_exp_f32_e32 v137, v137
	v_add_f32_e32 v136, 1.0, v136
	v_add_f32_e32 v137, 1.0, v137
	v_rcp_f32_e32 v136, v136
	v_rcp_f32_e32 v137, v137
	v_mul_f32_e32 v27, v27, v136
	v_mul_f32_e32 v11, v11, v137
	v_cvt_pk_bf16_f32 v138, v27, v11
	ds_write_b16 v197, v138 offset:13184
	ds_write_b16_d16_hi v197, v138 offset:13248
	ds_read_b128 v[128:131], v196 offset:224
	s_waitcnt lgkmcnt(0)
	v_mul_f32_e32 v60, v60, v128
	v_mul_f32_e32 v44, v44, v128
	v_mul_f32_e32 v132, 0xbfb8aa3b, v60
	v_mul_f32_e32 v133, 0xbfb8aa3b, v44
	v_exp_f32_e32 v132, v132
	v_exp_f32_e32 v133, v133
	v_add_f32_e32 v132, 1.0, v132
	v_add_f32_e32 v133, 1.0, v133
	v_rcp_f32_e32 v132, v132
	v_rcp_f32_e32 v133, v133
	v_mul_f32_e32 v60, v60, v132
	v_mul_f32_e32 v44, v44, v133
	v_cvt_pk_bf16_f32 v134, v60, v44
	ds_write_b16 v197, v134 offset:14336
	ds_write_b16_d16_hi v197, v134 offset:14400
	v_mul_f32_e32 v28, v28, v128
	v_mul_f32_e32 v12, v12, v128
	v_mul_f32_e32 v136, 0xbfb8aa3b, v28
	v_mul_f32_e32 v137, 0xbfb8aa3b, v12
	v_exp_f32_e32 v136, v136
	v_exp_f32_e32 v137, v137
	v_add_f32_e32 v136, 1.0, v136
	v_add_f32_e32 v137, 1.0, v137
	v_rcp_f32_e32 v136, v136
	v_rcp_f32_e32 v137, v137
	v_mul_f32_e32 v28, v28, v136
	v_mul_f32_e32 v12, v12, v137
	v_cvt_pk_bf16_f32 v138, v28, v12
	ds_write_b16 v197, v138 offset:14464
	ds_write_b16_d16_hi v197, v138 offset:14528
	v_mul_f32_e32 v61, v61, v129
	v_mul_f32_e32 v45, v45, v129
	v_mul_f32_e32 v132, 0xbfb8aa3b, v61
	v_mul_f32_e32 v133, 0xbfb8aa3b, v45
	v_exp_f32_e32 v132, v132
	v_exp_f32_e32 v133, v133
	v_add_f32_e32 v132, 1.0, v132
	v_add_f32_e32 v133, 1.0, v133
	v_rcp_f32_e32 v132, v132
	v_rcp_f32_e32 v133, v133
	v_mul_f32_e32 v61, v61, v132
	v_mul_f32_e32 v45, v45, v133
	v_cvt_pk_bf16_f32 v134, v61, v45
	ds_write_b16 v197, v134 offset:14592
	ds_write_b16_d16_hi v197, v134 offset:14656
	v_mul_f32_e32 v29, v29, v129
	v_mul_f32_e32 v13, v13, v129
	v_mul_f32_e32 v136, 0xbfb8aa3b, v29
	v_mul_f32_e32 v137, 0xbfb8aa3b, v13
	v_exp_f32_e32 v136, v136
	v_exp_f32_e32 v137, v137
	v_add_f32_e32 v136, 1.0, v136
	v_add_f32_e32 v137, 1.0, v137
	v_rcp_f32_e32 v136, v136
	v_rcp_f32_e32 v137, v137
	v_mul_f32_e32 v29, v29, v136
	v_mul_f32_e32 v13, v13, v137
	v_cvt_pk_bf16_f32 v138, v29, v13
	ds_write_b16 v197, v138 offset:14720
	ds_write_b16_d16_hi v197, v138 offset:14784
	v_mul_f32_e32 v62, v62, v130
	v_mul_f32_e32 v46, v46, v130
	v_mul_f32_e32 v132, 0xbfb8aa3b, v62
	v_mul_f32_e32 v133, 0xbfb8aa3b, v46
	v_exp_f32_e32 v132, v132
	v_exp_f32_e32 v133, v133
	v_add_f32_e32 v132, 1.0, v132
	v_add_f32_e32 v133, 1.0, v133
	v_rcp_f32_e32 v132, v132
	v_rcp_f32_e32 v133, v133
	v_mul_f32_e32 v62, v62, v132
	v_mul_f32_e32 v46, v46, v133
	v_cvt_pk_bf16_f32 v134, v62, v46
	ds_write_b16 v197, v134 offset:14848
	ds_write_b16_d16_hi v197, v134 offset:14912
	v_mul_f32_e32 v30, v30, v130
	v_mul_f32_e32 v14, v14, v130
	v_mul_f32_e32 v136, 0xbfb8aa3b, v30
	v_mul_f32_e32 v137, 0xbfb8aa3b, v14
	v_exp_f32_e32 v136, v136
	v_exp_f32_e32 v137, v137
	v_add_f32_e32 v136, 1.0, v136
	v_add_f32_e32 v137, 1.0, v137
	v_rcp_f32_e32 v136, v136
	v_rcp_f32_e32 v137, v137
	v_mul_f32_e32 v30, v30, v136
	v_mul_f32_e32 v14, v14, v137
	v_cvt_pk_bf16_f32 v138, v30, v14
	ds_write_b16 v197, v138 offset:14976
	ds_write_b16_d16_hi v197, v138 offset:15040
	v_mul_f32_e32 v63, v63, v131
	v_mul_f32_e32 v47, v47, v131
	v_mul_f32_e32 v132, 0xbfb8aa3b, v63
	v_mul_f32_e32 v133, 0xbfb8aa3b, v47
	v_exp_f32_e32 v132, v132
	v_exp_f32_e32 v133, v133
	v_add_f32_e32 v132, 1.0, v132
	v_add_f32_e32 v133, 1.0, v133
	v_rcp_f32_e32 v132, v132
	v_rcp_f32_e32 v133, v133
	v_mul_f32_e32 v63, v63, v132
	v_mul_f32_e32 v47, v47, v133
	v_cvt_pk_bf16_f32 v134, v63, v47
	ds_write_b16 v197, v134 offset:15104
	ds_write_b16_d16_hi v197, v134 offset:15168
	v_mul_f32_e32 v31, v31, v131
	v_mul_f32_e32 v15, v15, v131
	v_mul_f32_e32 v136, 0xbfb8aa3b, v31
	v_mul_f32_e32 v137, 0xbfb8aa3b, v15
	v_exp_f32_e32 v136, v136
	v_exp_f32_e32 v137, v137
	v_add_f32_e32 v136, 1.0, v136
	v_add_f32_e32 v137, 1.0, v137
	v_rcp_f32_e32 v136, v136
	v_rcp_f32_e32 v137, v137
	v_mul_f32_e32 v31, v31, v136
	v_mul_f32_e32 v15, v15, v137
	v_cvt_pk_bf16_f32 v138, v31, v15
	ds_write_b16 v197, v138 offset:15232
	ds_write_b16_d16_hi v197, v138 offset:15296
	s_waitcnt lgkmcnt(0)
; DI u16 f2bf(float a) { return (u16)(pack2(a, 0.f) & 0xffffu); }
; DI float siluf(float x) { return x * __builtin_amdgcn_rcpf(1.f + __expf(-x)); }
; template <bool TR>
; DI void gemm_in_tile(const P& p, int l, int id, char* smem) {
;     ...
;           p.AG[(size_t)tok * 512 + col] = f2bf(siluf(acc[rb][cb][reg] * rs));
	ds_read_b128 v[8:11], v249 offset:0
	ds_read_b128 v[12:15], v249 offset:1024
	ds_read_b128 v[16:19], v249 offset:2048
	ds_read_b128 v[20:23], v249 offset:3072
	ds_read_b128 v[24:27], v249 offset:4096
	ds_read_b128 v[28:31], v249 offset:5120
	ds_read_b128 v[32:35], v249 offset:6144
	ds_read_b128 v[36:39], v249 offset:7168
	ds_read_b128 v[40:43], v249 offset:8192
	ds_read_b128 v[44:47], v249 offset:9216
	ds_read_b128 v[48:51], v249 offset:10240
	ds_read_b128 v[52:55], v249 offset:11264
	ds_read_b128 v[56:59], v249 offset:12288
	ds_read_b128 v[60:63], v249 offset:13312
	ds_read_b128 v[64:67], v249 offset:14336
	ds_read_b128 v[68:71], v249 offset:15360
	s_waitcnt lgkmcnt(15)
	global_store_dwordx4 v250, v[8:11], s[30:31]
	v_add_u32_e32 v250, 0x1000, v250
	s_waitcnt lgkmcnt(14)
	global_store_dwordx4 v250, v[12:15], s[30:31]
	v_add_u32_e32 v250, 0x1000, v250
	s_waitcnt lgkmcnt(13)
	global_store_dwordx4 v250, v[16:19], s[30:31]
	v_add_u32_e32 v250, 0x1000, v250
	s_waitcnt lgkmcnt(12)
	global_store_dwordx4 v250, v[20:23], s[30:31]
	v_add_u32_e32 v250, 0x1000, v250
	s_waitcnt lgkmcnt(11)
	global_store_dwordx4 v250, v[24:27], s[30:31]
	v_add_u32_e32 v250, 0x1000, v250
	s_waitcnt lgkmcnt(10)
	global_store_dwordx4 v250, v[28:31], s[30:31]
	v_add_u32_e32 v250, 0x1000, v250
	s_waitcnt lgkmcnt(9)
	global_store_dwordx4 v250, v[32:35], s[30:31]
	v_add_u32_e32 v250, 0x1000, v250
	s_waitcnt lgkmcnt(8)
	global_store_dwordx4 v250, v[36:39], s[30:31]
	v_add_u32_e32 v250, 0x1000, v250
	s_waitcnt lgkmcnt(7)
	global_store_dwordx4 v250, v[40:43], s[30:31]
	v_add_u32_e32 v250, 0x1000, v250
	s_waitcnt lgkmcnt(6)
	global_store_dwordx4 v250, v[44:47], s[30:31]
	v_add_u32_e32 v250, 0x1000, v250
	s_waitcnt lgkmcnt(5)
	global_store_dwordx4 v250, v[48:51], s[30:31]
	v_add_u32_e32 v250, 0x1000, v250
	s_waitcnt lgkmcnt(4)
	global_store_dwordx4 v250, v[52:55], s[30:31]
	v_add_u32_e32 v250, 0x1000, v250
	s_waitcnt lgkmcnt(3)
	global_store_dwordx4 v250, v[56:59], s[30:31]
	v_add_u32_e32 v250, 0x1000, v250
	s_waitcnt lgkmcnt(2)
	global_store_dwordx4 v250, v[60:63], s[30:31]
	v_add_u32_e32 v250, 0x1000, v250
	s_waitcnt lgkmcnt(1)
	global_store_dwordx4 v250, v[64:67], s[30:31]
	v_add_u32_e32 v250, 0x1000, v250
	s_waitcnt lgkmcnt(0)
	global_store_dwordx4 v250, v[68:71], s[30:31]
	s_branch .LBB0_337

; template <bool AT>
; DI void gemm_main(f32x16 (&acc)[2][4], const u16* __restrict__ R, int ldr, const u16* __restrict__ Cm, int ldc,
;                   const u16* __restrict__ RT, int ldrt, int K, char* smem, int tid) {
;     ...
;   for (int kt = -1; kt < nk; ++kt) {
;     if (kt + 1 < nk) {
;       const int ks1 = kt + 1;
;       u16* Rs = S0 + (ks1 & 1) * STG;
;       u16* Cs = Rs + 256 * 72;
; #pragma unroll
;       for (int i = 0; i < 4; ++i) {
;         const int cid = tid + NT * i;
;         const int row = cid >> 3, kc = cid & 7;
;         if (AT && ks1 < 8) {
;           const int kr = cid >> 5, tc = cid & 31;
;           *(u32x4*)(Rs + kr * 264 + tc * 8) = rr[i];
;         } else {
;           *(u32x4*)(Rs + row * 72 + kc * 8) = rr[i];
;         }
;         *(u32x4*)(Cs + row * 72 + kc * 8) = cr[i];
;       }
;     }
;     if (kt + 2 < nk) {
;       const int kn = kt + 2;
; #pragma unroll
;       for (int i = 0; i < 4; ++i) {
;         const int cid = tid + NT * i;
;         const int row = cid >> 3, kc = cid & 7;
;         if (AT && kn < 8) {
;           const int kr = cid >> 5, tc = cid & 31;
;           rr[i] = *(const u32x4*)(RT + (size_t)(kn * 64 + kr) * ldrt + tc * 8);
;         } else {
;           rr[i] = *(const u32x4*)(R + (size_t)row * ldr + kn * 64 + kc * 8);
;         }
;         cr[i] = *(const u32x4*)(Cm + (size_t)row * ldc + kn * 64 + kc * 8);
;       }
;     }
;     __builtin_amdgcn_sched_barrier(0x38F);
;     if (kt >= 0) {
;       const u16* Rs = S0 + (kt & 1) * STG;
;       const u16* Cs = Rs + 256 * 72;
;       const u16* RTs = Rs;
; #pragma unroll
;       for (int ks = 0; ks < 4; ++ks) {
;         bf16x8 rf[2];
; #pragma unroll
;         for (int rb = 0; rb < 2; ++rb) {
;           if (AT && kt < 8) {
;             const u16* src = RTs + (16 * ks + 8 * g) * 264 + 64 * wr + 32 * rb + li;
;             bf16x8 t;
; #pragma unroll
;             for (int j = 0; j < 8; ++j) t[j] = (short)src[j * 264];
;             rf[rb] = t;
;           } else {
;             rf[rb] = *(const bf16x8*)(Rs + (64 * wr + 32 * rb + li) * 72 + 16 * ks + 8 * g);
;           }
;         }
; #pragma unroll
;         for (int cb = 0; cb < 4; ++cb) {
;           const bf16x8 cfv = *(const bf16x8*)(Cs + (128 * wc + 32 * cb + li) * 72 + 16 * ks + 8 * g);
; #pragma unroll
;           for (int rb = 0; rb < 2; ++rb) acc[rb][cb] = MFMA(rf[rb], cfv, acc[rb][cb]);
.Lgn_loop:
	ds_read_b128 v[192:195], v190 offset:0
	ds_read_b128 v[220:223], v190 offset:4608
	ds_read_b128 v[232:235], v191 offset:36864
	ds_read_b128 v[236:239], v191 offset:41472
	ds_read_b128 v[240:243], v191 offset:46080
	ds_read_b128 v[244:247], v191 offset:50688
	ds_read_b128 v[224:227], v190 offset:32
	ds_read_b128 v[228:231], v190 offset:4640
	s_waitcnt lgkmcnt(5)
	v_mfma_f32_32x32x16_bf16 v[112:127], v[192:195], v[232:235], v[112:127]
	v_mfma_f32_32x32x16_bf16 v[96:111], v[220:223], v[232:235], v[96:111]
	ds_read_b128 v[232:235], v191 offset:36896
	s_waitcnt vmcnt(0)
	ds_write_b128 v196, v[152:155]
	s_waitcnt lgkmcnt(6)
	v_mfma_f32_32x32x16_bf16 v[80:95], v[192:195], v[236:239], v[80:95]
	v_mfma_f32_32x32x16_bf16 v[64:79], v[220:223], v[236:239], v[64:79]
	ds_read_b128 v[236:239], v191 offset:41504
	ds_write_b128 v196, v[136:139] offset:36864
	s_waitcnt lgkmcnt(7)
	v_mfma_f32_32x32x16_bf16 v[48:63], v[192:195], v[240:243], v[48:63]
	v_mfma_f32_32x32x16_bf16 v[32:47], v[220:223], v[240:243], v[32:47]
	ds_read_b128 v[240:243], v191 offset:46112
	ds_write_b128 v197, v[148:151]
	s_waitcnt lgkmcnt(8)
	v_mfma_f32_32x32x16_bf16 v[16:31], v[192:195], v[244:247], v[16:31]
	v_mfma_f32_32x32x16_bf16 v[0:15], v[220:223], v[244:247], v[0:15]
	ds_read_b128 v[244:247], v191 offset:50720
	ds_write_b128 v197, v[132:135] offset:36864
	ds_read_b128 v[192:195], v190 offset:64
	ds_read_b128 v[220:223], v190 offset:4672
	s_waitcnt lgkmcnt(9)
	v_mfma_f32_32x32x16_bf16 v[112:127], v[224:227], v[232:235], v[112:127]
	v_mfma_f32_32x32x16_bf16 v[96:111], v[228:231], v[232:235], v[96:111]
	ds_read_b128 v[232:235], v191 offset:36928
	ds_write_b128 v249, v[144:147]
	s_waitcnt lgkmcnt(9)
	v_mfma_f32_32x32x16_bf16 v[80:95], v[224:227], v[236:239], v[80:95]
	v_mfma_f32_32x32x16_bf16 v[64:79], v[228:231], v[236:239], v[64:79]
	ds_read_b128 v[236:239], v191 offset:41536
	ds_write_b128 v249, v[128:131] offset:36864
	s_waitcnt lgkmcnt(9)
	v_mfma_f32_32x32x16_bf16 v[48:63], v[224:227], v[240:243], v[48:63]
	v_mfma_f32_32x32x16_bf16 v[32:47], v[228:231], v[240:243], v[32:47]
	ds_read_b128 v[240:243], v191 offset:46144
	ds_write_b128 v250, v[140:143]
	s_waitcnt lgkmcnt(9)
	v_mfma_f32_32x32x16_bf16 v[16:31], v[224:227], v[244:247], v[16:31]
	v_mfma_f32_32x32x16_bf16 v[0:15], v[228:231], v[244:247], v[0:15]
	ds_read_b128 v[244:247], v191 offset:50752
	ds_write_b128 v250, v[156:159] offset:36864
	ds_read_b128 v[224:227], v190 offset:96
	ds_read_b128 v[228:231], v190 offset:4704
	s_waitcnt lgkmcnt(9)
	v_mfma_f32_32x32x16_bf16 v[112:127], v[192:195], v[232:235], v[112:127]
	v_mfma_f32_32x32x16_bf16 v[96:111], v[220:223], v[232:235], v[96:111]
	ds_read_b128 v[232:235], v191 offset:36960
	v_subrev_u32_e32 v196, 0x12000, v196
	global_load_dwordx4 v[152:155], v[174:175], off
	s_waitcnt lgkmcnt(8)
	v_mfma_f32_32x32x16_bf16 v[80:95], v[192:195], v[236:239], v[80:95]
	v_mfma_f32_32x32x16_bf16 v[64:79], v[220:223], v[236:239], v[64:79]
	ds_read_b128 v[236:239], v191 offset:41568
	v_subrev_u32_e32 v197, 0x12000, v197
	global_load_dwordx4 v[136:139], v[166:167], off
	s_waitcnt lgkmcnt(7)
	v_mfma_f32_32x32x16_bf16 v[48:63], v[192:195], v[240:243], v[48:63]
	v_mfma_f32_32x32x16_bf16 v[32:47], v[220:223], v[240:243], v[32:47]
	ds_read_b128 v[240:243], v191 offset:46176
	v_subrev_u32_e32 v249, 0x12000, v249
	global_load_dwordx4 v[148:151], v[172:173], off
	s_waitcnt lgkmcnt(6)
	v_mfma_f32_32x32x16_bf16 v[16:31], v[192:195], v[244:247], v[16:31]
	v_mfma_f32_32x32x16_bf16 v[0:15], v[220:223], v[244:247], v[0:15]
	ds_read_b128 v[244:247], v191 offset:50784
	v_subrev_u32_e32 v250, 0x12000, v250
	global_load_dwordx4 v[132:135], v[164:165], off
	v_add_u32_e32 v190, 0x12000, v190
	v_add_u32_e32 v191, 0x12000, v191
	s_waitcnt lgkmcnt(3)
	v_mfma_f32_32x32x16_bf16 v[112:127], v[224:227], v[232:235], v[112:127]
	v_mfma_f32_32x32x16_bf16 v[96:111], v[228:231], v[232:235], v[96:111]
	global_load_dwordx4 v[144:147], v[170:171], off
	s_waitcnt lgkmcnt(2)
	v_mfma_f32_32x32x16_bf16 v[80:95], v[224:227], v[236:239], v[80:95]
	v_mfma_f32_32x32x16_bf16 v[64:79], v[228:231], v[236:239], v[64:79]
	global_load_dwordx4 v[128:131], v[162:163], off
	s_waitcnt lgkmcnt(1)
	v_mfma_f32_32x32x16_bf16 v[48:63], v[224:227], v[240:243], v[48:63]
	v_mfma_f32_32x32x16_bf16 v[32:47], v[228:231], v[240:243], v[32:47]
	global_load_dwordx4 v[140:143], v[168:169], off
	s_waitcnt lgkmcnt(0)
	v_mfma_f32_32x32x16_bf16 v[16:31], v[224:227], v[244:247], v[16:31]
	v_mfma_f32_32x32x16_bf16 v[0:15], v[228:231], v[244:247], v[0:15]
	global_load_dwordx4 v[156:159], v[160:161], off
	s_waitcnt lgkmcnt(0)
	s_barrier
; template <bool AT>
; DI void gemm_main(f32x16 (&acc)[2][4], const u16* __restrict__ R, int ldr, const u16* __restrict__ Cm, int ldc,
;                   const u16* __restrict__ RT, int ldrt, int K, char* smem, int tid) {
;     ...
;   for (int kt = -1; kt < nk; ++kt) {
;     if (kt + 1 < nk) {
;       const int ks1 = kt + 1;
;       u16* Rs = S0 + (ks1 & 1) * STG;
;       u16* Cs = Rs + 256 * 72;
; #pragma unroll
;       for (int i = 0; i < 4; ++i) {
;         const int cid = tid + NT * i;
;         const int row = cid >> 3, kc = cid & 7;
;         if (AT && ks1 < 8) {
;           const int kr = cid >> 5, tc = cid & 31;
;           *(u32x4*)(Rs + kr * 264 + tc * 8) = rr[i];
;         } else {
;           *(u32x4*)(Rs + row * 72 + kc * 8) = rr[i];
;         }
;         *(u32x4*)(Cs + row * 72 + kc * 8) = cr[i];
;       }
;     }
;     if (kt + 2 < nk) {
;       const int kn = kt + 2;
; #pragma unroll
;       for (int i = 0; i < 4; ++i) {
;         const int cid = tid + NT * i;
;         const int row = cid >> 3, kc = cid & 7;
;         if (AT && kn < 8) {
;           const int kr = cid >> 5, tc = cid & 31;
;           rr[i] = *(const u32x4*)(RT + (size_t)(kn * 64 + kr) * ldrt + tc * 8);
;         } else {
;           rr[i] = *(const u32x4*)(R + (size_t)row * ldr + kn * 64 + kc * 8);
;         }
;         cr[i] = *(const u32x4*)(Cm + (size_t)row * ldc + kn * 64 + kc * 8);
;       }
;     }
;     __builtin_amdgcn_sched_barrier(0x38F);
;     if (kt >= 0) {
;       const u16* Rs = S0 + (kt & 1) * STG;
;       const u16* Cs = Rs + 256 * 72;
;       const u16* RTs = Rs;
; #pragma unroll
;       for (int ks = 0; ks < 4; ++ks) {
;         bf16x8 rf[2];
; #pragma unroll
;         for (int rb = 0; rb < 2; ++rb) {
;           if (AT && kt < 8) {
;             const u16* src = RTs + (16 * ks + 8 * g) * 264 + 64 * wr + 32 * rb + li;
;             bf16x8 t;
; #pragma unroll
;             for (int j = 0; j < 8; ++j) t[j] = (short)src[j * 264];
;             rf[rb] = t;
;           } else {
;             rf[rb] = *(const bf16x8*)(Rs + (64 * wr + 32 * rb + li) * 72 + 16 * ks + 8 * g);
;           }
;         }
; #pragma unroll
;         for (int cb = 0; cb < 4; ++cb) {
;           const bf16x8 cfv = *(const bf16x8*)(Cs + (128 * wc + 32 * cb + li) * 72 + 16 * ks + 8 * g);
; #pragma unroll
;           for (int rb = 0; rb < 2; ++rb) acc[rb][cb] = MFMA(rf[rb], cfv, acc[rb][cb]);
	ds_read_b128 v[192:195], v190 offset:0
	ds_read_b128 v[220:223], v190 offset:4608
	ds_read_b128 v[232:235], v191 offset:36864
	ds_read_b128 v[236:239], v191 offset:41472
	ds_read_b128 v[240:243], v191 offset:46080
	ds_read_b128 v[244:247], v191 offset:50688
	ds_read_b128 v[224:227], v190 offset:32
	ds_read_b128 v[228:231], v190 offset:4640
	s_waitcnt lgkmcnt(5)
	v_mfma_f32_32x32x16_bf16 v[112:127], v[192:195], v[232:235], v[112:127]
	v_mfma_f32_32x32x16_bf16 v[96:111], v[220:223], v[232:235], v[96:111]
	ds_read_b128 v[232:235], v191 offset:36896
	s_waitcnt vmcnt(0)
	ds_write_b128 v196, v[152:155]
	s_waitcnt lgkmcnt(6)
	v_mfma_f32_32x32x16_bf16 v[80:95], v[192:195], v[236:239], v[80:95]
	v_mfma_f32_32x32x16_bf16 v[64:79], v[220:223], v[236:239], v[64:79]
	ds_read_b128 v[236:239], v191 offset:41504
	ds_write_b128 v196, v[136:139] offset:36864
	s_waitcnt lgkmcnt(7)
	v_mfma_f32_32x32x16_bf16 v[48:63], v[192:195], v[240:243], v[48:63]
	v_mfma_f32_32x32x16_bf16 v[32:47], v[220:223], v[240:243], v[32:47]
	ds_read_b128 v[240:243], v191 offset:46112
	ds_write_b128 v197, v[148:151]
	s_waitcnt lgkmcnt(8)
	v_mfma_f32_32x32x16_bf16 v[16:31], v[192:195], v[244:247], v[16:31]
	v_mfma_f32_32x32x16_bf16 v[0:15], v[220:223], v[244:247], v[0:15]
	ds_read_b128 v[244:247], v191 offset:50720
	ds_write_b128 v197, v[132:135] offset:36864
	ds_read_b128 v[192:195], v190 offset:64
	ds_read_b128 v[220:223], v190 offset:4672
	s_waitcnt lgkmcnt(9)
	v_mfma_f32_32x32x16_bf16 v[112:127], v[224:227], v[232:235], v[112:127]
	v_mfma_f32_32x32x16_bf16 v[96:111], v[228:231], v[232:235], v[96:111]
	ds_read_b128 v[232:235], v191 offset:36928
	ds_write_b128 v249, v[144:147]
	s_waitcnt lgkmcnt(9)
	v_mfma_f32_32x32x16_bf16 v[80:95], v[224:227], v[236:239], v[80:95]
	v_mfma_f32_32x32x16_bf16 v[64:79], v[228:231], v[236:239], v[64:79]
	ds_read_b128 v[236:239], v191 offset:41536
	ds_write_b128 v249, v[128:131] offset:36864
	s_waitcnt lgkmcnt(9)
	v_mfma_f32_32x32x16_bf16 v[48:63], v[224:227], v[240:243], v[48:63]
	v_mfma_f32_32x32x16_bf16 v[32:47], v[228:231], v[240:243], v[32:47]
	ds_read_b128 v[240:243], v191 offset:46144
	ds_write_b128 v250, v[140:143]
	s_waitcnt lgkmcnt(9)
	v_mfma_f32_32x32x16_bf16 v[16:31], v[224:227], v[244:247], v[16:31]
	v_mfma_f32_32x32x16_bf16 v[0:15], v[228:231], v[244:247], v[0:15]
	ds_read_b128 v[244:247], v191 offset:50752
	ds_write_b128 v250, v[156:159] offset:36864
	ds_read_b128 v[224:227], v190 offset:96
	ds_read_b128 v[228:231], v190 offset:4704
	s_waitcnt lgkmcnt(9)
	v_mfma_f32_32x32x16_bf16 v[112:127], v[192:195], v[232:235], v[112:127]
	v_mfma_f32_32x32x16_bf16 v[96:111], v[220:223], v[232:235], v[96:111]
	ds_read_b128 v[232:235], v191 offset:36960
	v_add_u32_e32 v196, 0x12000, v196
	global_load_dwordx4 v[152:155], v[174:175], off offset:128
	v_lshl_add_u64 v[174:175], s[58:59], 1, v[174:175]
	s_waitcnt lgkmcnt(8)
	v_mfma_f32_32x32x16_bf16 v[80:95], v[192:195], v[236:239], v[80:95]
	v_mfma_f32_32x32x16_bf16 v[64:79], v[220:223], v[236:239], v[64:79]
	ds_read_b128 v[236:239], v191 offset:41568
	v_add_u32_e32 v197, 0x12000, v197
	global_load_dwordx4 v[136:139], v[166:167], off offset:128
	v_lshl_add_u64 v[166:167], s[58:59], 1, v[166:167]
	s_waitcnt lgkmcnt(7)
	v_mfma_f32_32x32x16_bf16 v[48:63], v[192:195], v[240:243], v[48:63]
	v_mfma_f32_32x32x16_bf16 v[32:47], v[220:223], v[240:243], v[32:47]
	ds_read_b128 v[240:243], v191 offset:46176
	v_add_u32_e32 v249, 0x12000, v249
	global_load_dwordx4 v[148:151], v[172:173], off offset:128
	v_lshl_add_u64 v[172:173], s[58:59], 1, v[172:173]
	s_waitcnt lgkmcnt(6)
	v_mfma_f32_32x32x16_bf16 v[16:31], v[192:195], v[244:247], v[16:31]
	v_mfma_f32_32x32x16_bf16 v[0:15], v[220:223], v[244:247], v[0:15]
	ds_read_b128 v[244:247], v191 offset:50784
	v_add_u32_e32 v250, 0x12000, v250
	global_load_dwordx4 v[132:135], v[164:165], off offset:128
	v_lshl_add_u64 v[164:165], s[58:59], 1, v[164:165]
	v_subrev_u32_e32 v190, 0x12000, v190
	v_subrev_u32_e32 v191, 0x12000, v191
	s_waitcnt lgkmcnt(3)
	v_mfma_f32_32x32x16_bf16 v[112:127], v[224:227], v[232:235], v[112:127]
	v_mfma_f32_32x32x16_bf16 v[96:111], v[228:231], v[232:235], v[96:111]
	global_load_dwordx4 v[144:147], v[170:171], off offset:128
	v_lshl_add_u64 v[170:171], s[58:59], 1, v[170:171]
	s_waitcnt lgkmcnt(2)
	v_mfma_f32_32x32x16_bf16 v[80:95], v[224:227], v[236:239], v[80:95]
	v_mfma_f32_32x32x16_bf16 v[64:79], v[228:231], v[236:239], v[64:79]
	global_load_dwordx4 v[128:131], v[162:163], off offset:128
	v_lshl_add_u64 v[162:163], s[58:59], 1, v[162:163]
	s_waitcnt lgkmcnt(1)
	v_mfma_f32_32x32x16_bf16 v[48:63], v[224:227], v[240:243], v[48:63]
	v_mfma_f32_32x32x16_bf16 v[32:47], v[228:231], v[240:243], v[32:47]
	global_load_dwordx4 v[140:143], v[168:169], off offset:128
	v_lshl_add_u64 v[168:169], s[58:59], 1, v[168:169]
	s_waitcnt lgkmcnt(0)
	v_mfma_f32_32x32x16_bf16 v[16:31], v[224:227], v[244:247], v[16:31]
	v_mfma_f32_32x32x16_bf16 v[0:15], v[228:231], v[244:247], v[0:15]
	global_load_dwordx4 v[156:159], v[160:161], off offset:128
	v_lshl_add_u64 v[160:161], s[58:59], 1, v[160:161]
	s_waitcnt lgkmcnt(0)
	s_barrier
	s_add_i32 s64, s64, -1
	s_cmp_lg_u32 s64, 0
	s_cbranch_scc1 .Lgn_loop
; template <bool AT>
; DI void gemm_main(f32x16 (&acc)[2][4], const u16* __restrict__ R, int ldr, const u16* __restrict__ Cm, int ldc,
;                   const u16* __restrict__ RT, int ldrt, int K, char* smem, int tid) {
;     ...
;   for (int kt = -1; kt < nk; ++kt) {
;     if (kt + 1 < nk) {
;       const int ks1 = kt + 1;
;       u16* Rs = S0 + (ks1 & 1) * STG;
;       u16* Cs = Rs + 256 * 72;
; #pragma unroll
;       for (int i = 0; i < 4; ++i) {
;         const int cid = tid + NT * i;
;         const int row = cid >> 3, kc = cid & 7;
;         if (AT && ks1 < 8) {
;           const int kr = cid >> 5, tc = cid & 31;
;           *(u32x4*)(Rs + kr * 264 + tc * 8) = rr[i];
;         } else {
;           *(u32x4*)(Rs + row * 72 + kc * 8) = rr[i];
;         }
;         *(u32x4*)(Cs + row * 72 + kc * 8) = cr[i];
;       }
;     }
;     if (kt + 2 < nk) {
;       const int kn = kt + 2;
; #pragma unroll
;       for (int i = 0; i < 4; ++i) {
;         const int cid = tid + NT * i;
;         const int row = cid >> 3, kc = cid & 7;
;         if (AT && kn < 8) {
;           const int kr = cid >> 5, tc = cid & 31;
;           rr[i] = *(const u32x4*)(RT + (size_t)(kn * 64 + kr) * ldrt + tc * 8);
;         } else {
;           rr[i] = *(const u32x4*)(R + (size_t)row * ldr + kn * 64 + kc * 8);
;         }
;         cr[i] = *(const u32x4*)(Cm + (size_t)row * ldc + kn * 64 + kc * 8);
;       }
;     }
;     __builtin_amdgcn_sched_barrier(0x38F);
;     if (kt >= 0) {
;       const u16* Rs = S0 + (kt & 1) * STG;
;       const u16* Cs = Rs + 256 * 72;
;       const u16* RTs = Rs;
; #pragma unroll
;       for (int ks = 0; ks < 4; ++ks) {
;         bf16x8 rf[2];
; #pragma unroll
;         for (int rb = 0; rb < 2; ++rb) {
;           if (AT && kt < 8) {
;             const u16* src = RTs + (16 * ks + 8 * g) * 264 + 64 * wr + 32 * rb + li;
;             bf16x8 t;
; #pragma unroll
;             for (int j = 0; j < 8; ++j) t[j] = (short)src[j * 264];
;             rf[rb] = t;
;           } else {
;             rf[rb] = *(const bf16x8*)(Rs + (64 * wr + 32 * rb + li) * 72 + 16 * ks + 8 * g);
;           }
;         }
; #pragma unroll
;         for (int cb = 0; cb < 4; ++cb) {
;           const bf16x8 cfv = *(const bf16x8*)(Cs + (128 * wc + 32 * cb + li) * 72 + 16 * ks + 8 * g);
; #pragma unroll
;           for (int rb = 0; rb < 2; ++rb) acc[rb][cb] = MFMA(rf[rb], cfv, acc[rb][cb]);
	ds_read_b128 v[192:195], v190 offset:0
	ds_read_b128 v[220:223], v190 offset:4608
	ds_read_b128 v[232:235], v191 offset:36864
	ds_read_b128 v[236:239], v191 offset:41472
	ds_read_b128 v[240:243], v191 offset:46080
	ds_read_b128 v[244:247], v191 offset:50688
	ds_read_b128 v[224:227], v190 offset:32
	ds_read_b128 v[228:231], v190 offset:4640
	s_waitcnt lgkmcnt(5)
	v_mfma_f32_32x32x16_bf16 v[112:127], v[192:195], v[232:235], v[112:127]
	v_mfma_f32_32x32x16_bf16 v[96:111], v[220:223], v[232:235], v[96:111]
	ds_read_b128 v[232:235], v191 offset:36896
	s_waitcnt vmcnt(0)
	ds_write_b128 v196, v[152:155]
	s_waitcnt lgkmcnt(6)
	v_mfma_f32_32x32x16_bf16 v[80:95], v[192:195], v[236:239], v[80:95]
	v_mfma_f32_32x32x16_bf16 v[64:79], v[220:223], v[236:239], v[64:79]
	ds_read_b128 v[236:239], v191 offset:41504
	ds_write_b128 v196, v[136:139] offset:36864
	s_waitcnt lgkmcnt(7)
	v_mfma_f32_32x32x16_bf16 v[48:63], v[192:195], v[240:243], v[48:63]
	v_mfma_f32_32x32x16_bf16 v[32:47], v[220:223], v[240:243], v[32:47]
	ds_read_b128 v[240:243], v191 offset:46112
	ds_write_b128 v197, v[148:151]
	s_waitcnt lgkmcnt(8)
	v_mfma_f32_32x32x16_bf16 v[16:31], v[192:195], v[244:247], v[16:31]
	v_mfma_f32_32x32x16_bf16 v[0:15], v[220:223], v[244:247], v[0:15]
	ds_read_b128 v[244:247], v191 offset:50720
	ds_write_b128 v197, v[132:135] offset:36864
	ds_read_b128 v[192:195], v190 offset:64
	ds_read_b128 v[220:223], v190 offset:4672
	s_waitcnt lgkmcnt(9)
	v_mfma_f32_32x32x16_bf16 v[112:127], v[224:227], v[232:235], v[112:127]
	v_mfma_f32_32x32x16_bf16 v[96:111], v[228:231], v[232:235], v[96:111]
	ds_read_b128 v[232:235], v191 offset:36928
	ds_write_b128 v249, v[144:147]
	s_waitcnt lgkmcnt(9)
	v_mfma_f32_32x32x16_bf16 v[80:95], v[224:227], v[236:239], v[80:95]
	v_mfma_f32_32x32x16_bf16 v[64:79], v[228:231], v[236:239], v[64:79]
	ds_read_b128 v[236:239], v191 offset:41536
	ds_write_b128 v249, v[128:131] offset:36864
	s_waitcnt lgkmcnt(9)
	v_mfma_f32_32x32x16_bf16 v[48:63], v[224:227], v[240:243], v[48:63]
	v_mfma_f32_32x32x16_bf16 v[32:47], v[228:231], v[240:243], v[32:47]
	ds_read_b128 v[240:243], v191 offset:46144
	ds_write_b128 v250, v[140:143]
	s_waitcnt lgkmcnt(9)
	v_mfma_f32_32x32x16_bf16 v[16:31], v[224:227], v[244:247], v[16:31]
	v_mfma_f32_32x32x16_bf16 v[0:15], v[228:231], v[244:247], v[0:15]
	ds_read_b128 v[244:247], v191 offset:50752
	ds_write_b128 v250, v[156:159] offset:36864
	ds_read_b128 v[224:227], v190 offset:96
	ds_read_b128 v[228:231], v190 offset:4704
	s_waitcnt lgkmcnt(9)
	v_mfma_f32_32x32x16_bf16 v[112:127], v[192:195], v[232:235], v[112:127]
	v_mfma_f32_32x32x16_bf16 v[96:111], v[220:223], v[232:235], v[96:111]
	ds_read_b128 v[232:235], v191 offset:36960
	v_subrev_u32_e32 v196, 0x12000, v196
	s_waitcnt lgkmcnt(8)
	v_mfma_f32_32x32x16_bf16 v[80:95], v[192:195], v[236:239], v[80:95]
	v_mfma_f32_32x32x16_bf16 v[64:79], v[220:223], v[236:239], v[64:79]
	ds_read_b128 v[236:239], v191 offset:41568
	v_subrev_u32_e32 v197, 0x12000, v197
	s_waitcnt lgkmcnt(7)
	v_mfma_f32_32x32x16_bf16 v[48:63], v[192:195], v[240:243], v[48:63]
	v_mfma_f32_32x32x16_bf16 v[32:47], v[220:223], v[240:243], v[32:47]
	ds_read_b128 v[240:243], v191 offset:46176
	v_subrev_u32_e32 v249, 0x12000, v249
	s_waitcnt lgkmcnt(6)
	v_mfma_f32_32x32x16_bf16 v[16:31], v[192:195], v[244:247], v[16:31]
	v_mfma_f32_32x32x16_bf16 v[0:15], v[220:223], v[244:247], v[0:15]
	ds_read_b128 v[244:247], v191 offset:50784
	v_subrev_u32_e32 v250, 0x12000, v250
	v_add_u32_e32 v190, 0x12000, v190
	v_add_u32_e32 v191, 0x12000, v191
	s_waitcnt lgkmcnt(3)
	v_mfma_f32_32x32x16_bf16 v[112:127], v[224:227], v[232:235], v[112:127]
	v_mfma_f32_32x32x16_bf16 v[96:111], v[228:231], v[232:235], v[96:111]
	s_waitcnt lgkmcnt(2)
	v_mfma_f32_32x32x16_bf16 v[80:95], v[224:227], v[236:239], v[80:95]
	v_mfma_f32_32x32x16_bf16 v[64:79], v[228:231], v[236:239], v[64:79]
	s_waitcnt lgkmcnt(1)
	v_mfma_f32_32x32x16_bf16 v[48:63], v[224:227], v[240:243], v[48:63]
	v_mfma_f32_32x32x16_bf16 v[32:47], v[228:231], v[240:243], v[32:47]
	s_waitcnt lgkmcnt(0)
	v_mfma_f32_32x32x16_bf16 v[16:31], v[224:227], v[244:247], v[16:31]
	v_mfma_f32_32x32x16_bf16 v[0:15], v[228:231], v[244:247], v[0:15]
	s_waitcnt lgkmcnt(0)
	s_barrier
	ds_read_b128 v[192:195], v190 offset:0
	ds_read_b128 v[220:223], v190 offset:4608
	ds_read_b128 v[232:235], v191 offset:36864
	ds_read_b128 v[236:239], v191 offset:41472
	ds_read_b128 v[240:243], v191 offset:46080
	ds_read_b128 v[244:247], v191 offset:50688
	ds_read_b128 v[224:227], v190 offset:32
	ds_read_b128 v[228:231], v190 offset:4640
	s_waitcnt lgkmcnt(5)
	v_mfma_f32_32x32x16_bf16 v[112:127], v[192:195], v[232:235], v[112:127]
	v_mfma_f32_32x32x16_bf16 v[96:111], v[220:223], v[232:235], v[96:111]
	ds_read_b128 v[232:235], v191 offset:36896
	s_waitcnt lgkmcnt(5)
	v_mfma_f32_32x32x16_bf16 v[80:95], v[192:195], v[236:239], v[80:95]
	v_mfma_f32_32x32x16_bf16 v[64:79], v[220:223], v[236:239], v[64:79]
	ds_read_b128 v[236:239], v191 offset:41504
	s_waitcnt lgkmcnt(5)
	v_mfma_f32_32x32x16_bf16 v[48:63], v[192:195], v[240:243], v[48:63]
	v_mfma_f32_32x32x16_bf16 v[32:47], v[220:223], v[240:243], v[32:47]
	ds_read_b128 v[240:243], v191 offset:46112
	s_waitcnt lgkmcnt(5)
	v_mfma_f32_32x32x16_bf16 v[16:31], v[192:195], v[244:247], v[16:31]
	v_mfma_f32_32x32x16_bf16 v[0:15], v[220:223], v[244:247], v[0:15]
	ds_read_b128 v[244:247], v191 offset:50720
	ds_read_b128 v[192:195], v190 offset:64
	ds_read_b128 v[220:223], v190 offset:4672
	s_waitcnt lgkmcnt(5)
	v_mfma_f32_32x32x16_bf16 v[112:127], v[224:227], v[232:235], v[112:127]
	v_mfma_f32_32x32x16_bf16 v[96:111], v[228:231], v[232:235], v[96:111]
	ds_read_b128 v[232:235], v191 offset:36928
	s_waitcnt lgkmcnt(5)
; #define MFMA(a, b, c) __builtin_amdgcn_mfma_f32_32x32x16_bf16((a), (b), (c), 0, 0, 0)
; DI u16 f2bf(float a) { return (u16)(pack2(a, 0.f) & 0xffffu); }
; DI int crow(int reg, int g) { return (reg & 3) + 8 * (reg >> 2) + 4 * g; }
; template <bool AT>
; DI void gemm_main(f32x16 (&acc)[2][4], const u16* __restrict__ R, int ldr, const u16* __restrict__ Cm, int ldc,
;                   const u16* __restrict__ RT, int ldrt, int K, char* smem, int tid) {
;     ...
;     if (kt >= 0) {
;       const u16* Rs = S0 + (kt & 1) * STG;
;       const u16* Cs = Rs + 256 * 72;
;       const u16* RTs = Rs;
; #pragma unroll
;       for (int ks = 0; ks < 4; ++ks) {
;         bf16x8 rf[2];
; #pragma unroll
;         for (int rb = 0; rb < 2; ++rb) {
;           if (AT && kt < 8) {
;             const u16* src = RTs + (16 * ks + 8 * g) * 264 + 64 * wr + 32 * rb + li;
;             bf16x8 t;
; #pragma unroll
;             for (int j = 0; j < 8; ++j) t[j] = (short)src[j * 264];
;             rf[rb] = t;
;           } else {
;             rf[rb] = *(const bf16x8*)(Rs + (64 * wr + 32 * rb + li) * 72 + 16 * ks + 8 * g);
;           }
;         }
; #pragma unroll
;         for (int cb = 0; cb < 4; ++cb) {
;           const bf16x8 cfv = *(const bf16x8*)(Cs + (128 * wc + 32 * cb + li) * 72 + 16 * ks + 8 * g);
; #pragma unroll
;           for (int rb = 0; rb < 2; ++rb) acc[rb][cb] = MFMA(rf[rb], cfv, acc[rb][cb]);
;         }
;       }
;     }
;     __syncthreads();
; template <bool TR>
; DI void gemm_in_tile(const P& p, int l, int id, char* smem) {
;     ...
;   if (tr) {
;     const bool hy = nt < 8;
; #pragma unroll
;     for (int cb = 0; cb < 4; ++cb) {
;       asm volatile("" ::: "memory");
;       const int tl = 128 * wc + 32 * cb + li;
;       const int tok = m0 + tl;
;       const float rs = rs_s[tl];
;       u16* dst = hy ? (p.hyT + (size_t)(n0 + 64 * wr) * HYP + tok)
;                     : (p.VT + (size_t)((tok >> 13) * 512 + (n0 - 3072) + 64 * wr) * VTP + (tok & 8191));
;       const size_t cstride = hy ? (size_t)HYP : (size_t)VTP;
; #pragma unroll
;       for (int rb = 0; rb < 2; ++rb) {
; #pragma unroll
;         for (int reg = 0; reg < 16; ++reg) {
;           const int cl = 32 * rb + crow(reg, g);
;           dst[(size_t)cl * cstride] = f2bf(acc[rb][cb][reg] * rs);
;         }
	v_mfma_f32_32x32x16_bf16 v[80:95], v[224:227], v[236:239], v[80:95]
	v_mfma_f32_32x32x16_bf16 v[64:79], v[228:231], v[236:239], v[64:79]
	ds_read_b128 v[236:239], v191 offset:41536
	s_waitcnt lgkmcnt(5)
	v_mfma_f32_32x32x16_bf16 v[48:63], v[224:227], v[240:243], v[48:63]
	v_mfma_f32_32x32x16_bf16 v[32:47], v[228:231], v[240:243], v[32:47]
	ds_read_b128 v[240:243], v191 offset:46144
	s_waitcnt lgkmcnt(5)
	v_mfma_f32_32x32x16_bf16 v[16:31], v[224:227], v[244:247], v[16:31]
	v_mfma_f32_32x32x16_bf16 v[0:15], v[228:231], v[244:247], v[0:15]
	ds_read_b128 v[244:247], v191 offset:50752
	ds_read_b128 v[224:227], v190 offset:96
	ds_read_b128 v[228:231], v190 offset:4704
	s_waitcnt lgkmcnt(5)
	v_mfma_f32_32x32x16_bf16 v[112:127], v[192:195], v[232:235], v[112:127]
	v_mfma_f32_32x32x16_bf16 v[96:111], v[220:223], v[232:235], v[96:111]
	ds_read_b128 v[232:235], v191 offset:36960
	v_add_u32_e32 v196, 0x12000, v196
	s_waitcnt lgkmcnt(5)
	v_mfma_f32_32x32x16_bf16 v[80:95], v[192:195], v[236:239], v[80:95]
	v_mfma_f32_32x32x16_bf16 v[64:79], v[220:223], v[236:239], v[64:79]
	ds_read_b128 v[236:239], v191 offset:41568
	v_add_u32_e32 v197, 0x12000, v197
	s_waitcnt lgkmcnt(5)
	v_mfma_f32_32x32x16_bf16 v[48:63], v[192:195], v[240:243], v[48:63]
	v_mfma_f32_32x32x16_bf16 v[32:47], v[220:223], v[240:243], v[32:47]
	ds_read_b128 v[240:243], v191 offset:46176
	v_add_u32_e32 v249, 0x12000, v249
	s_waitcnt lgkmcnt(5)
	v_mfma_f32_32x32x16_bf16 v[16:31], v[192:195], v[244:247], v[16:31]
	v_mfma_f32_32x32x16_bf16 v[0:15], v[220:223], v[244:247], v[0:15]
	ds_read_b128 v[244:247], v191 offset:50784
	v_add_u32_e32 v250, 0x12000, v250
	v_subrev_u32_e32 v190, 0x12000, v190
	v_subrev_u32_e32 v191, 0x12000, v191
	s_waitcnt lgkmcnt(3)
	v_mfma_f32_32x32x16_bf16 v[112:127], v[224:227], v[232:235], v[112:127]
	v_mfma_f32_32x32x16_bf16 v[96:111], v[228:231], v[232:235], v[96:111]
	s_waitcnt lgkmcnt(2)
	v_mfma_f32_32x32x16_bf16 v[80:95], v[224:227], v[236:239], v[80:95]
	v_mfma_f32_32x32x16_bf16 v[64:79], v[228:231], v[236:239], v[64:79]
	s_waitcnt lgkmcnt(1)
	v_mfma_f32_32x32x16_bf16 v[48:63], v[224:227], v[240:243], v[48:63]
	v_mfma_f32_32x32x16_bf16 v[32:47], v[228:231], v[240:243], v[32:47]
	s_waitcnt lgkmcnt(0)
	v_mfma_f32_32x32x16_bf16 v[16:31], v[224:227], v[244:247], v[16:31]
	v_mfma_f32_32x32x16_bf16 v[0:15], v[228:231], v[244:247], v[0:15]
	s_waitcnt lgkmcnt(0)
	s_barrier
	s_nop 7
	v_mov_b32_e32 v162, s56
	s_lshl_b32 s9, s75, 4
	s_and_b32 s9, s9, 0x200
	s_add_i32 s9, s8, s9
	s_addk_i32 s9, 0xf400
	v_lshrrev_b32_e32 v128, 3, v177
	v_and_b32_e32 v163, 4, v128
	v_add_u32_e32 v130, s9, v178
	s_movk_i32 s9, 0x4080
	v_add_u32_e32 v132, s8, v178
	s_add_i32 s8, 0, 0x24000
	v_lshl_add_u32 v128, v176, 2, s8
	ds_read_b32 v164, v128
	v_mov_b64_e32 v[128:129], s[28:29]
	v_mad_i64_i32 v[128:129], s[10:11], v130, s9, v[128:129]
	s_movk_i32 s9, 0x1f9f
	v_or_b32_e32 v133, s56, v176
	v_bitop3_b32 v134, v176, s9, v162 bitop3:0xc8
	v_mov_b64_e32 v[130:131], s[38:39]
	s_and_b64 s[10:11], s[6:7], exec
	s_movk_i32 s9, 0x4040
	v_mad_i64_i32 v[130:131], s[10:11], v132, s67, v[130:131]
	v_cndmask_b32_e64 v132, v134, v133, s[6:7]
	s_cselect_b32 s9, s9, 0x2040
	v_cndmask_b32_e64 v129, v129, v131, s[6:7]
	v_cndmask_b32_e64 v128, v128, v130, s[6:7]
	v_lshlrev_b32_e32 v188, 1, v132
	v_mul_u32_u24_e32 v130, s9, v163
	v_lshl_add_u64 v[138:139], v[128:129], 0, v[188:189]
	v_readfirstlane_b32 s98, v138
	v_readfirstlane_b32 s99, v139
	s_lshl_b32 s100, s9, 1
	s_lshl_b32 s101, s9, 3
	v_and_b32_e32 v144, 63, v198
	v_lshrrev_b32_e32 v145, 6, v198
	v_mul_u32_u24_e32 v145, 0x4400, v145
	v_lshrrev_b32_e32 v146, 5, v144
	v_mul_u32_u24_e32 v146, 0x440, v146
	v_and_b32_e32 v147, 31, v144
	v_lshl_add_u32 v148, v147, 1, v146
	v_add_u32_e32 v148, v148, v145
	v_lshrrev_b32_e32 v146, 4, v144
	v_and_b32_e32 v147, 15, v144
	v_mul_u32_u24_e32 v149, 0x110, v146
	v_lshl_add_u32 v149, v147, 4, v149
	v_add_u32_e32 v149, v149, v145
	v_mul_lo_u32 v150, v146, s100
	v_lshl_add_u32 v150, v147, 4, v150
	v_lshl_add_u32 v151, v176, 2, s8
	ds_read_b32 v140, v151 offset:0
	ds_read_b32 v141, v151 offset:128
	ds_read_b32 v142, v151 offset:256
	ds_read_b32 v143, v151 offset:384
	s_waitcnt lgkmcnt(0)
	v_mul_f32_e32 v112, v112, v140
	v_mul_f32_e32 v113, v113, v140
	v_cvt_pk_bf16_f32 v152, v112, v113
	ds_write_b16 v148, v152 offset:0
	v_lshrrev_b32_e32 v152, 16, v152
	ds_write_b16 v148, v152 offset:272
	v_mul_f32_e32 v114, v114, v140
	v_mul_f32_e32 v115, v115, v140
	v_cvt_pk_bf16_f32 v153, v114, v115
	ds_write_b16 v148, v153 offset:544
	v_lshrrev_b32_e32 v153, 16, v153
	ds_write_b16 v148, v153 offset:816
	v_mul_f32_e32 v116, v116, v140
	v_mul_f32_e32 v117, v117, v140
	v_cvt_pk_bf16_f32 v154, v116, v117
	ds_write_b16 v148, v154 offset:2176
	v_lshrrev_b32_e32 v154, 16, v154
	ds_write_b16 v148, v154 offset:2448
	v_mul_f32_e32 v118, v118, v140
	v_mul_f32_e32 v119, v119, v140
	v_cvt_pk_bf16_f32 v155, v118, v119
	ds_write_b16 v148, v155 offset:2720
	v_lshrrev_b32_e32 v155, 16, v155
	ds_write_b16 v148, v155 offset:2992
	v_mul_f32_e32 v120, v120, v140
	v_mul_f32_e32 v121, v121, v140
	v_cvt_pk_bf16_f32 v156, v120, v121
	ds_write_b16 v148, v156 offset:4352
	v_lshrrev_b32_e32 v156, 16, v156
	ds_write_b16 v148, v156 offset:4624
	v_mul_f32_e32 v122, v122, v140
	v_mul_f32_e32 v123, v123, v140
	v_cvt_pk_bf16_f32 v157, v122, v123
	ds_write_b16 v148, v157 offset:4896
	v_lshrrev_b32_e32 v157, 16, v157
	ds_write_b16 v148, v157 offset:5168
	v_mul_f32_e32 v124, v124, v140
	v_mul_f32_e32 v125, v125, v140
	v_cvt_pk_bf16_f32 v158, v124, v125
	ds_write_b16 v148, v158 offset:6528
	v_lshrrev_b32_e32 v158, 16, v158
	ds_write_b16 v148, v158 offset:6800
; DI u16 f2bf(float a) { return (u16)(pack2(a, 0.f) & 0xffffu); }
; DI int crow(int reg, int g) { return (reg & 3) + 8 * (reg >> 2) + 4 * g; }
; template <bool TR>
; DI void gemm_in_tile(const P& p, int l, int id, char* smem) {
;     ...
;   if (tr) {
;     const bool hy = nt < 8;
; #pragma unroll
;     for (int cb = 0; cb < 4; ++cb) {
;       asm volatile("" ::: "memory");
;       const int tl = 128 * wc + 32 * cb + li;
;       const int tok = m0 + tl;
;       const float rs = rs_s[tl];
;       u16* dst = hy ? (p.hyT + (size_t)(n0 + 64 * wr) * HYP + tok)
;                     : (p.VT + (size_t)((tok >> 13) * 512 + (n0 - 3072) + 64 * wr) * VTP + (tok & 8191));
;       const size_t cstride = hy ? (size_t)HYP : (size_t)VTP;
; #pragma unroll
;       for (int rb = 0; rb < 2; ++rb) {
; #pragma unroll
;         for (int reg = 0; reg < 16; ++reg) {
;           const int cl = 32 * rb + crow(reg, g);
;           dst[(size_t)cl * cstride] = f2bf(acc[rb][cb][reg] * rs);
;         }
;       }
;     }
	v_mul_f32_e32 v126, v126, v140
	v_mul_f32_e32 v127, v127, v140
	v_cvt_pk_bf16_f32 v159, v126, v127
	ds_write_b16 v148, v159 offset:7072
	v_lshrrev_b32_e32 v159, 16, v159
	ds_write_b16 v148, v159 offset:7344
	v_mul_f32_e32 v96, v96, v140
	v_mul_f32_e32 v97, v97, v140
	v_cvt_pk_bf16_f32 v152, v96, v97
	ds_write_b16 v148, v152 offset:8704
	v_lshrrev_b32_e32 v152, 16, v152
	ds_write_b16 v148, v152 offset:8976
	v_mul_f32_e32 v98, v98, v140
	v_mul_f32_e32 v99, v99, v140
	v_cvt_pk_bf16_f32 v153, v98, v99
	ds_write_b16 v148, v153 offset:9248
	v_lshrrev_b32_e32 v153, 16, v153
	ds_write_b16 v148, v153 offset:9520
	v_mul_f32_e32 v100, v100, v140
	v_mul_f32_e32 v101, v101, v140
	v_cvt_pk_bf16_f32 v154, v100, v101
	ds_write_b16 v148, v154 offset:10880
	v_lshrrev_b32_e32 v154, 16, v154
	ds_write_b16 v148, v154 offset:11152
	v_mul_f32_e32 v102, v102, v140
	v_mul_f32_e32 v103, v103, v140
	v_cvt_pk_bf16_f32 v155, v102, v103
	ds_write_b16 v148, v155 offset:11424
	v_lshrrev_b32_e32 v155, 16, v155
	ds_write_b16 v148, v155 offset:11696
	v_mul_f32_e32 v104, v104, v140
	v_mul_f32_e32 v105, v105, v140
	v_cvt_pk_bf16_f32 v156, v104, v105
	ds_write_b16 v148, v156 offset:13056
	v_lshrrev_b32_e32 v156, 16, v156
	ds_write_b16 v148, v156 offset:13328
	v_mul_f32_e32 v106, v106, v140
	v_mul_f32_e32 v107, v107, v140
	v_cvt_pk_bf16_f32 v157, v106, v107
	ds_write_b16 v148, v157 offset:13600
	v_lshrrev_b32_e32 v157, 16, v157
	ds_write_b16 v148, v157 offset:13872
	v_mul_f32_e32 v108, v108, v140
	v_mul_f32_e32 v109, v109, v140
	v_cvt_pk_bf16_f32 v158, v108, v109
	ds_write_b16 v148, v158 offset:15232
	v_lshrrev_b32_e32 v158, 16, v158
	ds_write_b16 v148, v158 offset:15504
	v_mul_f32_e32 v110, v110, v140
	v_mul_f32_e32 v111, v111, v140
	v_cvt_pk_bf16_f32 v159, v110, v111
	ds_write_b16 v148, v159 offset:15776
	v_lshrrev_b32_e32 v159, 16, v159
	ds_write_b16 v148, v159 offset:16048
	v_mul_f32_e32 v80, v80, v141
	v_mul_f32_e32 v81, v81, v141
	v_cvt_pk_bf16_f32 v152, v80, v81
	ds_write_b16 v148, v152 offset:64
	v_lshrrev_b32_e32 v152, 16, v152
	ds_write_b16 v148, v152 offset:336
	v_mul_f32_e32 v82, v82, v141
	v_mul_f32_e32 v83, v83, v141
	v_cvt_pk_bf16_f32 v153, v82, v83
	ds_write_b16 v148, v153 offset:608
	v_lshrrev_b32_e32 v153, 16, v153
	ds_write_b16 v148, v153 offset:880
	v_mul_f32_e32 v84, v84, v141
	v_mul_f32_e32 v85, v85, v141
	v_cvt_pk_bf16_f32 v154, v84, v85
	ds_write_b16 v148, v154 offset:2240
	v_lshrrev_b32_e32 v154, 16, v154
	ds_write_b16 v148, v154 offset:2512
	v_mul_f32_e32 v86, v86, v141
	v_mul_f32_e32 v87, v87, v141
	v_cvt_pk_bf16_f32 v155, v86, v87
	ds_write_b16 v148, v155 offset:2784
	v_lshrrev_b32_e32 v155, 16, v155
	ds_write_b16 v148, v155 offset:3056
	v_mul_f32_e32 v88, v88, v141
	v_mul_f32_e32 v89, v89, v141
	v_cvt_pk_bf16_f32 v156, v88, v89
	ds_write_b16 v148, v156 offset:4416
	v_lshrrev_b32_e32 v156, 16, v156
	ds_write_b16 v148, v156 offset:4688
	v_mul_f32_e32 v90, v90, v141
	v_mul_f32_e32 v91, v91, v141
	v_cvt_pk_bf16_f32 v157, v90, v91
	ds_write_b16 v148, v157 offset:4960
	v_lshrrev_b32_e32 v157, 16, v157
	ds_write_b16 v148, v157 offset:5232
	v_mul_f32_e32 v92, v92, v141
	v_mul_f32_e32 v93, v93, v141
	v_cvt_pk_bf16_f32 v158, v92, v93
	ds_write_b16 v148, v158 offset:6592
	v_lshrrev_b32_e32 v158, 16, v158
	ds_write_b16 v148, v158 offset:6864
	v_mul_f32_e32 v94, v94, v141
	v_mul_f32_e32 v95, v95, v141
	v_cvt_pk_bf16_f32 v159, v94, v95
	ds_write_b16 v148, v159 offset:7136
	v_lshrrev_b32_e32 v159, 16, v159
	ds_write_b16 v148, v159 offset:7408
	v_mul_f32_e32 v64, v64, v141
	v_mul_f32_e32 v65, v65, v141
	v_cvt_pk_bf16_f32 v152, v64, v65
	ds_write_b16 v148, v152 offset:8768
	v_lshrrev_b32_e32 v152, 16, v152
	ds_write_b16 v148, v152 offset:9040
	v_mul_f32_e32 v66, v66, v141
	v_mul_f32_e32 v67, v67, v141
	v_cvt_pk_bf16_f32 v153, v66, v67
	ds_write_b16 v148, v153 offset:9312
	v_lshrrev_b32_e32 v153, 16, v153
	ds_write_b16 v148, v153 offset:9584
	v_mul_f32_e32 v68, v68, v141
	v_mul_f32_e32 v69, v69, v141
	v_cvt_pk_bf16_f32 v154, v68, v69
	ds_write_b16 v148, v154 offset:10944
	v_lshrrev_b32_e32 v154, 16, v154
	ds_write_b16 v148, v154 offset:11216
	v_mul_f32_e32 v70, v70, v141
	v_mul_f32_e32 v71, v71, v141
	v_cvt_pk_bf16_f32 v155, v70, v71
	ds_write_b16 v148, v155 offset:11488
	v_lshrrev_b32_e32 v155, 16, v155
	ds_write_b16 v148, v155 offset:11760
	v_mul_f32_e32 v72, v72, v141
	v_mul_f32_e32 v73, v73, v141
	v_cvt_pk_bf16_f32 v156, v72, v73
	ds_write_b16 v148, v156 offset:13120
	v_lshrrev_b32_e32 v156, 16, v156
	ds_write_b16 v148, v156 offset:13392
	v_mul_f32_e32 v74, v74, v141
	v_mul_f32_e32 v75, v75, v141
	v_cvt_pk_bf16_f32 v157, v74, v75
	ds_write_b16 v148, v157 offset:13664
	v_lshrrev_b32_e32 v157, 16, v157
	ds_write_b16 v148, v157 offset:13936
	v_mul_f32_e32 v76, v76, v141
	v_mul_f32_e32 v77, v77, v141
	v_cvt_pk_bf16_f32 v158, v76, v77
	ds_write_b16 v148, v158 offset:15296
	v_lshrrev_b32_e32 v158, 16, v158
	ds_write_b16 v148, v158 offset:15568
	v_mul_f32_e32 v78, v78, v141
	v_mul_f32_e32 v79, v79, v141
	v_cvt_pk_bf16_f32 v159, v78, v79
	ds_write_b16 v148, v159 offset:15840
	v_lshrrev_b32_e32 v159, 16, v159
	ds_write_b16 v148, v159 offset:16112
	v_mul_f32_e32 v48, v48, v142
	v_mul_f32_e32 v49, v49, v142
	v_cvt_pk_bf16_f32 v152, v48, v49
	ds_write_b16 v148, v152 offset:128
	v_lshrrev_b32_e32 v152, 16, v152
	ds_write_b16 v148, v152 offset:400
	v_mul_f32_e32 v50, v50, v142
	v_mul_f32_e32 v51, v51, v142
	v_cvt_pk_bf16_f32 v153, v50, v51
	ds_write_b16 v148, v153 offset:672
	v_lshrrev_b32_e32 v153, 16, v153
	ds_write_b16 v148, v153 offset:944
	v_mul_f32_e32 v52, v52, v142
	v_mul_f32_e32 v53, v53, v142
	v_cvt_pk_bf16_f32 v154, v52, v53
	ds_write_b16 v148, v154 offset:2304
; DI u16 f2bf(float a) { return (u16)(pack2(a, 0.f) & 0xffffu); }
; DI int crow(int reg, int g) { return (reg & 3) + 8 * (reg >> 2) + 4 * g; }
; template <bool TR>
; DI void gemm_in_tile(const P& p, int l, int id, char* smem) {
;     ...
;   if (tr) {
;     const bool hy = nt < 8;
; #pragma unroll
;     for (int cb = 0; cb < 4; ++cb) {
;       asm volatile("" ::: "memory");
;       const int tl = 128 * wc + 32 * cb + li;
;       const int tok = m0 + tl;
;       const float rs = rs_s[tl];
;       u16* dst = hy ? (p.hyT + (size_t)(n0 + 64 * wr) * HYP + tok)
;                     : (p.VT + (size_t)((tok >> 13) * 512 + (n0 - 3072) + 64 * wr) * VTP + (tok & 8191));
;       const size_t cstride = hy ? (size_t)HYP : (size_t)VTP;
; #pragma unroll
;       for (int rb = 0; rb < 2; ++rb) {
; #pragma unroll
;         for (int reg = 0; reg < 16; ++reg) {
;           const int cl = 32 * rb + crow(reg, g);
;           dst[(size_t)cl * cstride] = f2bf(acc[rb][cb][reg] * rs);
;         }
;       }
;     }
	v_lshrrev_b32_e32 v154, 16, v154
	ds_write_b16 v148, v154 offset:2576
	v_mul_f32_e32 v54, v54, v142
	v_mul_f32_e32 v55, v55, v142
	v_cvt_pk_bf16_f32 v155, v54, v55
	ds_write_b16 v148, v155 offset:2848
	v_lshrrev_b32_e32 v155, 16, v155
	ds_write_b16 v148, v155 offset:3120
	v_mul_f32_e32 v56, v56, v142
	v_mul_f32_e32 v57, v57, v142
	v_cvt_pk_bf16_f32 v156, v56, v57
	ds_write_b16 v148, v156 offset:4480
	v_lshrrev_b32_e32 v156, 16, v156
	ds_write_b16 v148, v156 offset:4752
	v_mul_f32_e32 v58, v58, v142
	v_mul_f32_e32 v59, v59, v142
	v_cvt_pk_bf16_f32 v157, v58, v59
	ds_write_b16 v148, v157 offset:5024
	v_lshrrev_b32_e32 v157, 16, v157
	ds_write_b16 v148, v157 offset:5296
	v_mul_f32_e32 v60, v60, v142
	v_mul_f32_e32 v61, v61, v142
	v_cvt_pk_bf16_f32 v158, v60, v61
	ds_write_b16 v148, v158 offset:6656
	v_lshrrev_b32_e32 v158, 16, v158
	ds_write_b16 v148, v158 offset:6928
	v_mul_f32_e32 v62, v62, v142
	v_mul_f32_e32 v63, v63, v142
	v_cvt_pk_bf16_f32 v159, v62, v63
	ds_write_b16 v148, v159 offset:7200
	v_lshrrev_b32_e32 v159, 16, v159
	ds_write_b16 v148, v159 offset:7472
	v_mul_f32_e32 v32, v32, v142
	v_mul_f32_e32 v33, v33, v142
	v_cvt_pk_bf16_f32 v152, v32, v33
	ds_write_b16 v148, v152 offset:8832
	v_lshrrev_b32_e32 v152, 16, v152
	ds_write_b16 v148, v152 offset:9104
	v_mul_f32_e32 v34, v34, v142
	v_mul_f32_e32 v35, v35, v142
	v_cvt_pk_bf16_f32 v153, v34, v35
	ds_write_b16 v148, v153 offset:9376
	v_lshrrev_b32_e32 v153, 16, v153
	ds_write_b16 v148, v153 offset:9648
	v_mul_f32_e32 v36, v36, v142
	v_mul_f32_e32 v37, v37, v142
	v_cvt_pk_bf16_f32 v154, v36, v37
	ds_write_b16 v148, v154 offset:11008
	v_lshrrev_b32_e32 v154, 16, v154
	ds_write_b16 v148, v154 offset:11280
	v_mul_f32_e32 v38, v38, v142
	v_mul_f32_e32 v39, v39, v142
	v_cvt_pk_bf16_f32 v155, v38, v39
	ds_write_b16 v148, v155 offset:11552
	v_lshrrev_b32_e32 v155, 16, v155
	ds_write_b16 v148, v155 offset:11824
	v_mul_f32_e32 v40, v40, v142
	v_mul_f32_e32 v41, v41, v142
	v_cvt_pk_bf16_f32 v156, v40, v41
	ds_write_b16 v148, v156 offset:13184
	v_lshrrev_b32_e32 v156, 16, v156
	ds_write_b16 v148, v156 offset:13456
	v_mul_f32_e32 v42, v42, v142
	v_mul_f32_e32 v43, v43, v142
	v_cvt_pk_bf16_f32 v157, v42, v43
	ds_write_b16 v148, v157 offset:13728
	v_lshrrev_b32_e32 v157, 16, v157
	ds_write_b16 v148, v157 offset:14000
	v_mul_f32_e32 v44, v44, v142
	v_mul_f32_e32 v45, v45, v142
	v_cvt_pk_bf16_f32 v158, v44, v45
	ds_write_b16 v148, v158 offset:15360
	v_lshrrev_b32_e32 v158, 16, v158
	ds_write_b16 v148, v158 offset:15632
	v_mul_f32_e32 v46, v46, v142
	v_mul_f32_e32 v47, v47, v142
	v_cvt_pk_bf16_f32 v159, v46, v47
	ds_write_b16 v148, v159 offset:15904
	v_lshrrev_b32_e32 v159, 16, v159
	ds_write_b16 v148, v159 offset:16176
	v_mul_f32_e32 v16, v16, v143
	v_mul_f32_e32 v17, v17, v143
	v_cvt_pk_bf16_f32 v152, v16, v17
	ds_write_b16 v148, v152 offset:192
	v_lshrrev_b32_e32 v152, 16, v152
	ds_write_b16 v148, v152 offset:464
	v_mul_f32_e32 v18, v18, v143
	v_mul_f32_e32 v19, v19, v143
	v_cvt_pk_bf16_f32 v153, v18, v19
	ds_write_b16 v148, v153 offset:736
	v_lshrrev_b32_e32 v153, 16, v153
	ds_write_b16 v148, v153 offset:1008
	v_mul_f32_e32 v20, v20, v143
	v_mul_f32_e32 v21, v21, v143
	v_cvt_pk_bf16_f32 v154, v20, v21
	ds_write_b16 v148, v154 offset:2368
	v_lshrrev_b32_e32 v154, 16, v154
	ds_write_b16 v148, v154 offset:2640
	v_mul_f32_e32 v22, v22, v143
	v_mul_f32_e32 v23, v23, v143
	v_cvt_pk_bf16_f32 v155, v22, v23
	ds_write_b16 v148, v155 offset:2912
	v_lshrrev_b32_e32 v155, 16, v155
	ds_write_b16 v148, v155 offset:3184
	v_mul_f32_e32 v24, v24, v143
	v_mul_f32_e32 v25, v25, v143
	v_cvt_pk_bf16_f32 v156, v24, v25
	ds_write_b16 v148, v156 offset:4544
	v_lshrrev_b32_e32 v156, 16, v156
	ds_write_b16 v148, v156 offset:4816
	v_mul_f32_e32 v26, v26, v143
	v_mul_f32_e32 v27, v27, v143
	v_cvt_pk_bf16_f32 v157, v26, v27
	ds_write_b16 v148, v157 offset:5088
	v_lshrrev_b32_e32 v157, 16, v157
	ds_write_b16 v148, v157 offset:5360
	v_mul_f32_e32 v28, v28, v143
	v_mul_f32_e32 v29, v29, v143
	v_cvt_pk_bf16_f32 v158, v28, v29
	ds_write_b16 v148, v158 offset:6720
	v_lshrrev_b32_e32 v158, 16, v158
	ds_write_b16 v148, v158 offset:6992
	v_mul_f32_e32 v30, v30, v143
	v_mul_f32_e32 v31, v31, v143
	v_cvt_pk_bf16_f32 v159, v30, v31
	ds_write_b16 v148, v159 offset:7264
	v_lshrrev_b32_e32 v159, 16, v159
	ds_write_b16 v148, v159 offset:7536
	v_mul_f32_e32 v0, v0, v143
	v_mul_f32_e32 v1, v1, v143
	v_cvt_pk_bf16_f32 v152, v0, v1
	ds_write_b16 v148, v152 offset:8896
	v_lshrrev_b32_e32 v152, 16, v152
	ds_write_b16 v148, v152 offset:9168
	v_mul_f32_e32 v2, v2, v143
	v_mul_f32_e32 v3, v3, v143
	v_cvt_pk_bf16_f32 v153, v2, v3
	ds_write_b16 v148, v153 offset:9440
	v_lshrrev_b32_e32 v153, 16, v153
	ds_write_b16 v148, v153 offset:9712
	v_mul_f32_e32 v4, v4, v143
	v_mul_f32_e32 v5, v5, v143
	v_cvt_pk_bf16_f32 v154, v4, v5
	ds_write_b16 v148, v154 offset:11072
	v_lshrrev_b32_e32 v154, 16, v154
	ds_write_b16 v148, v154 offset:11344
	v_mul_f32_e32 v6, v6, v143
	v_mul_f32_e32 v7, v7, v143
	v_cvt_pk_bf16_f32 v155, v6, v7
	ds_write_b16 v148, v155 offset:11616
	v_lshrrev_b32_e32 v155, 16, v155
	ds_write_b16 v148, v155 offset:11888
	v_mul_f32_e32 v8, v8, v143
	v_mul_f32_e32 v9, v9, v143
	v_cvt_pk_bf16_f32 v156, v8, v9
	ds_write_b16 v148, v156 offset:13248
	v_lshrrev_b32_e32 v156, 16, v156
	ds_write_b16 v148, v156 offset:13520
	v_mul_f32_e32 v10, v10, v143
	v_mul_f32_e32 v11, v11, v143
	v_cvt_pk_bf16_f32 v157, v10, v11
	ds_write_b16 v148, v157 offset:13792
	v_lshrrev_b32_e32 v157, 16, v157
	ds_write_b16 v148, v157 offset:14064
	v_mul_f32_e32 v12, v12, v143
	v_mul_f32_e32 v13, v13, v143
	v_cvt_pk_bf16_f32 v158, v12, v13
	ds_write_b16 v148, v158 offset:15424
	v_lshrrev_b32_e32 v158, 16, v158
	ds_write_b16 v148, v158 offset:15696
	v_mul_f32_e32 v14, v14, v143
	v_mul_f32_e32 v15, v15, v143
	v_cvt_pk_bf16_f32 v159, v14, v15
	ds_write_b16 v148, v159 offset:15968
	v_lshrrev_b32_e32 v159, 16, v159
	ds_write_b16 v148, v159 offset:16240
	v_and_b32_e32 v162, 31, v144
	v_lshlrev_b32_e32 v162, 1, v162
	v_sub_u32_e32 v162, v150, v162
	v_mov_b32_e32 v163, 0
	v_lshl_add_u64 v[160:161], v[138:139], 0, v[162:163]
	s_mov_b32 s100, s101
	s_mov_b32 s101, 0
	s_waitcnt lgkmcnt(0)
; DI u16 f2bf(float a) { return (u16)(pack2(a, 0.f) & 0xffffu); }
; DI int crow(int reg, int g) { return (reg & 3) + 8 * (reg >> 2) + 4 * g; }
; template <bool TR>
; DI void gemm_in_tile(const P& p, int l, int id, char* smem) {
;     ...
;       u16* dst = hy ? (p.hyT + (size_t)(n0 + 64 * wr) * HYP + tok)
;                     : (p.VT + (size_t)((tok >> 13) * 512 + (n0 - 3072) + 64 * wr) * VTP + (tok & 8191));
;       const size_t cstride = hy ? (size_t)HYP : (size_t)VTP;
; #pragma unroll
;       for (int rb = 0; rb < 2; ++rb) {
; #pragma unroll
;         for (int reg = 0; reg < 16; ++reg) {
;           const int cl = 32 * rb + crow(reg, g);
;           dst[(size_t)cl * cstride] = f2bf(acc[rb][cb][reg] * rs);
;         }
;       }
	ds_read_b128 v[0:3], v149 offset:0
	ds_read_b128 v[4:7], v149 offset:1088
	ds_read_b128 v[8:11], v149 offset:2176
	ds_read_b128 v[12:15], v149 offset:3264
	ds_read_b128 v[16:19], v149 offset:4352
	ds_read_b128 v[20:23], v149 offset:5440
	ds_read_b128 v[24:27], v149 offset:6528
	ds_read_b128 v[28:31], v149 offset:7616
	ds_read_b128 v[32:35], v149 offset:8704
	ds_read_b128 v[36:39], v149 offset:9792
	ds_read_b128 v[40:43], v149 offset:10880
	ds_read_b128 v[44:47], v149 offset:11968
	ds_read_b128 v[48:51], v149 offset:13056
	ds_read_b128 v[52:55], v149 offset:14144
	ds_read_b128 v[56:59], v149 offset:15232
	ds_read_b128 v[60:63], v149 offset:16320
	s_waitcnt lgkmcnt(15)
	global_store_dwordx4 v[160:161], v[0:3], off
	v_lshl_add_u64 v[160:161], v[160:161], 0, s[100:101]
	s_waitcnt lgkmcnt(14)
	global_store_dwordx4 v[160:161], v[4:7], off
	v_lshl_add_u64 v[160:161], v[160:161], 0, s[100:101]
	s_waitcnt lgkmcnt(13)
	global_store_dwordx4 v[160:161], v[8:11], off
	v_lshl_add_u64 v[160:161], v[160:161], 0, s[100:101]
	s_waitcnt lgkmcnt(12)
	global_store_dwordx4 v[160:161], v[12:15], off
	v_lshl_add_u64 v[160:161], v[160:161], 0, s[100:101]
	s_waitcnt lgkmcnt(11)
	global_store_dwordx4 v[160:161], v[16:19], off
	v_lshl_add_u64 v[160:161], v[160:161], 0, s[100:101]
	s_waitcnt lgkmcnt(10)
	global_store_dwordx4 v[160:161], v[20:23], off
	v_lshl_add_u64 v[160:161], v[160:161], 0, s[100:101]
	s_waitcnt lgkmcnt(9)
	global_store_dwordx4 v[160:161], v[24:27], off
	v_lshl_add_u64 v[160:161], v[160:161], 0, s[100:101]
	s_waitcnt lgkmcnt(8)
	global_store_dwordx4 v[160:161], v[28:31], off
	v_lshl_add_u64 v[160:161], v[160:161], 0, s[100:101]
	s_waitcnt lgkmcnt(7)
	global_store_dwordx4 v[160:161], v[32:35], off
	v_lshl_add_u64 v[160:161], v[160:161], 0, s[100:101]
	s_waitcnt lgkmcnt(6)
	global_store_dwordx4 v[160:161], v[36:39], off
	v_lshl_add_u64 v[160:161], v[160:161], 0, s[100:101]
	s_waitcnt lgkmcnt(5)
	global_store_dwordx4 v[160:161], v[40:43], off
	v_lshl_add_u64 v[160:161], v[160:161], 0, s[100:101]
	s_waitcnt lgkmcnt(4)
	global_store_dwordx4 v[160:161], v[44:47], off
	v_lshl_add_u64 v[160:161], v[160:161], 0, s[100:101]
	s_waitcnt lgkmcnt(3)
	global_store_dwordx4 v[160:161], v[48:51], off
	v_lshl_add_u64 v[160:161], v[160:161], 0, s[100:101]
	s_waitcnt lgkmcnt(2)
	global_store_dwordx4 v[160:161], v[52:55], off
	v_lshl_add_u64 v[160:161], v[160:161], 0, s[100:101]
	s_waitcnt lgkmcnt(1)
	global_store_dwordx4 v[160:161], v[56:59], off
	v_lshl_add_u64 v[160:161], v[160:161], 0, s[100:101]
	s_waitcnt lgkmcnt(0)
	global_store_dwordx4 v[160:161], v[60:63], off
	s_branch .LBB0_102
